# 28 redundant post-barrier s_waitcnt lgkmcnt(0) removed from the 7 GEMM main loops
# speedup vs baseline: 1.0293x; 1.0033x over previous
.LBB0_245:
	s_add_u32 s18, s16, 0x100
	s_addc_u32 s19, s17, 0
	s_add_i32 s53, 0, 0x10000
	v_add_u32_e32 v94, s53, v80
	ds_read_b128 v[82:85], v94
	ds_read_b128 v[86:89], v94 offset:1024
	ds_read_b128 v[90:93], v94 offset:2048
	ds_read_b128 v[94:97], v94 offset:3072
	s_cmp_eq_u32 s52, 4
	s_cselect_b32 s23, s9, s19
	s_cselect_b32 s22, s8, s18
	s_cselect_b32 s21, s15, s47
	s_cselect_b32 s20, s45, s46
	v_lshl_add_u64 v[130:131], s[16:17], 0, v[76:77]
	s_add_i32 m0, s29, 0xc000
	ds_read_b128 v[98:101], v81
	ds_read_b128 v[102:105], v81 offset:1024
	ds_read_b128 v[106:109], v81 offset:2048
	ds_read_b128 v[110:113], v81 offset:3072
	ds_read_b128 v[114:117], v81 offset:4096
	ds_read_b128 v[118:121], v81 offset:5120
	ds_read_b128 v[122:125], v81 offset:6144
	ds_read_b128 v[126:129], v81 offset:7168
	global_load_lds_dwordx4 v[130:131], off
	v_lshl_add_u64 v[130:131], s[16:17], 0, v[78:79]
	s_add_i32 m0, s29, 0xe000
	s_nop 0
	global_load_lds_dwordx4 v[130:131], off
	s_waitcnt vmcnt(8)
	s_waitcnt lgkmcnt(0)
	s_barrier
	s_setprio 1
	v_mfma_f32_16x16x32_bf16 v[62:65], v[82:85], v[98:101], v[62:65]
	v_mfma_f32_16x16x32_bf16 v[58:61], v[90:93], v[98:101], v[58:61]
	v_mfma_f32_16x16x32_bf16 v[54:57], v[82:85], v[106:109], v[54:57]
	v_mfma_f32_16x16x32_bf16 v[50:53], v[90:93], v[106:109], v[50:53]
	v_mfma_f32_16x16x32_bf16 v[46:49], v[82:85], v[114:117], v[46:49]
	v_mfma_f32_16x16x32_bf16 v[42:45], v[90:93], v[114:117], v[42:45]
	v_mfma_f32_16x16x32_bf16 v[38:41], v[82:85], v[122:125], v[38:41]
	v_mfma_f32_16x16x32_bf16 v[34:37], v[90:93], v[122:125], v[34:37]
	v_mfma_f32_16x16x32_bf16 v[62:65], v[86:89], v[102:105], v[62:65]
	v_mfma_f32_16x16x32_bf16 v[58:61], v[94:97], v[102:105], v[58:61]
	v_mfma_f32_16x16x32_bf16 v[54:57], v[86:89], v[110:113], v[54:57]
	v_mfma_f32_16x16x32_bf16 v[50:53], v[94:97], v[110:113], v[50:53]
	v_mfma_f32_16x16x32_bf16 v[46:49], v[86:89], v[118:121], v[46:49]
	v_mfma_f32_16x16x32_bf16 v[42:45], v[94:97], v[118:121], v[42:45]
	v_mfma_f32_16x16x32_bf16 v[38:41], v[86:89], v[126:129], v[38:41]
	v_mfma_f32_16x16x32_bf16 v[34:37], v[94:97], v[126:129], v[34:37]
	s_setprio 0
	s_setprio 1
	s_setprio 0
	s_barrier
	s_add_i32 s16, s53, s28
	v_lshl_add_u64 v[130:131], s[20:21], 0, v[70:71]
	s_mov_b32 m0, s16
	ds_read_b128 v[98:101], v81 offset:16384
	ds_read_b128 v[102:105], v81 offset:17408
	ds_read_b128 v[106:109], v81 offset:18432
	ds_read_b128 v[110:113], v81 offset:19456
	ds_read_b128 v[114:117], v81 offset:20480
	ds_read_b128 v[118:121], v81 offset:21504
	ds_read_b128 v[122:125], v81 offset:22528
	ds_read_b128 v[126:129], v81 offset:23552
	global_load_lds_dwordx4 v[130:131], off
	s_add_i32 m0, s16, 0x2000
	s_add_u32 s16, s20, 0x20000
	v_lshl_add_u64 v[132:133], s[20:21], 0, v[66:67]
	s_addc_u32 s17, s21, 0
	global_load_lds_dwordx4 v[132:133], off
	v_lshl_add_u64 v[134:135], s[16:17], 0, v[70:71]
	s_mov_b32 m0, s30
	v_lshl_add_u64 v[136:137], s[22:23], 0, v[68:69]
	global_load_lds_dwordx4 v[134:135], off
	v_lshl_add_u64 v[134:135], s[16:17], 0, v[66:67]
	s_mov_b32 m0, s31
	s_nop 0
	global_load_lds_dwordx4 v[134:135], off
	v_lshl_add_u64 v[134:135], s[22:23], 0, v[72:73]
	s_mov_b32 m0, s29
	s_nop 0
	global_load_lds_dwordx4 v[134:135], off
	s_mov_b32 m0, s34
	s_nop 0
	global_load_lds_dwordx4 v[136:137], off
	s_waitcnt vmcnt(8)
	s_waitcnt lgkmcnt(0)
	s_barrier
	s_setprio 1
	v_mfma_f32_16x16x32_bf16 v[30:33], v[82:85], v[98:101], v[30:33]
	v_mfma_f32_16x16x32_bf16 v[26:29], v[90:93], v[98:101], v[26:29]
	v_mfma_f32_16x16x32_bf16 v[22:25], v[82:85], v[106:109], v[22:25]
	v_mfma_f32_16x16x32_bf16 v[18:21], v[90:93], v[106:109], v[18:21]
	v_mfma_f32_16x16x32_bf16 v[14:17], v[82:85], v[114:117], v[14:17]
	v_mfma_f32_16x16x32_bf16 v[10:13], v[90:93], v[114:117], v[10:13]
	v_mfma_f32_16x16x32_bf16 v[6:9], v[82:85], v[122:125], v[6:9]
	v_mfma_f32_16x16x32_bf16 v[2:5], v[90:93], v[122:125], v[2:5]
	v_mfma_f32_16x16x32_bf16 v[30:33], v[86:89], v[102:105], v[30:33]
	v_mfma_f32_16x16x32_bf16 v[26:29], v[94:97], v[102:105], v[26:29]
	v_mfma_f32_16x16x32_bf16 v[22:25], v[86:89], v[110:113], v[22:25]
	v_mfma_f32_16x16x32_bf16 v[18:21], v[94:97], v[110:113], v[18:21]
	v_mfma_f32_16x16x32_bf16 v[14:17], v[86:89], v[118:121], v[14:17]
	v_mfma_f32_16x16x32_bf16 v[10:13], v[94:97], v[118:121], v[10:13]
	v_mfma_f32_16x16x32_bf16 v[6:9], v[86:89], v[126:129], v[6:9]
	v_mfma_f32_16x16x32_bf16 v[2:5], v[94:97], v[126:129], v[2:5]
	s_setprio 0
	s_setprio 1
	s_setprio 0
	s_barrier
	s_add_i32 s53, 0, 0x18000
	v_add_u32_e32 v94, s53, v80
	ds_read_b128 v[82:85], v94
	ds_read_b128 v[86:89], v94 offset:1024
	ds_read_b128 v[90:93], v94 offset:2048
	ds_read_b128 v[94:97], v94 offset:3072
	s_add_u32 s16, s22, 0x28000
	s_addc_u32 s17, s23, 0
	s_mov_b32 m0, s35
	v_lshl_add_u64 v[138:139], s[16:17], 0, v[72:73]
	ds_read_b128 v[98:101], v81 offset:32768
	ds_read_b128 v[102:105], v81 offset:33792
	ds_read_b128 v[106:109], v81 offset:34816
	ds_read_b128 v[110:113], v81 offset:35840
	ds_read_b128 v[114:117], v81 offset:36864
	ds_read_b128 v[118:121], v81 offset:37888
	ds_read_b128 v[122:125], v81 offset:38912
	ds_read_b128 v[126:129], v81 offset:39936
	global_load_lds_dwordx4 v[138:139], off
	v_lshl_add_u64 v[138:139], s[16:17], 0, v[68:69]
	s_mov_b32 m0, s36
	s_nop 0
	global_load_lds_dwordx4 v[138:139], off
	s_waitcnt vmcnt(8)
	s_waitcnt lgkmcnt(0)
	s_barrier
	s_setprio 1
	v_mfma_f32_16x16x32_bf16 v[62:65], v[82:85], v[98:101], v[62:65]
	v_mfma_f32_16x16x32_bf16 v[58:61], v[90:93], v[98:101], v[58:61]
	v_mfma_f32_16x16x32_bf16 v[54:57], v[82:85], v[106:109], v[54:57]
	v_mfma_f32_16x16x32_bf16 v[50:53], v[90:93], v[106:109], v[50:53]
	v_mfma_f32_16x16x32_bf16 v[46:49], v[82:85], v[114:117], v[46:49]
	v_mfma_f32_16x16x32_bf16 v[42:45], v[90:93], v[114:117], v[42:45]
	v_mfma_f32_16x16x32_bf16 v[38:41], v[82:85], v[122:125], v[38:41]
	v_mfma_f32_16x16x32_bf16 v[34:37], v[90:93], v[122:125], v[34:37]
	v_mfma_f32_16x16x32_bf16 v[62:65], v[86:89], v[102:105], v[62:65]
	v_mfma_f32_16x16x32_bf16 v[58:61], v[94:97], v[102:105], v[58:61]
	v_mfma_f32_16x16x32_bf16 v[54:57], v[86:89], v[110:113], v[54:57]
	v_mfma_f32_16x16x32_bf16 v[50:53], v[94:97], v[110:113], v[50:53]
	v_mfma_f32_16x16x32_bf16 v[46:49], v[86:89], v[118:121], v[46:49]
	v_mfma_f32_16x16x32_bf16 v[42:45], v[94:97], v[118:121], v[42:45]
	v_mfma_f32_16x16x32_bf16 v[38:41], v[86:89], v[126:129], v[38:41]
	v_mfma_f32_16x16x32_bf16 v[34:37], v[94:97], v[126:129], v[34:37]
	s_setprio 0
	s_setprio 1
	s_setprio 0
	s_barrier
	s_add_i32 s16, s53, s28
	v_lshl_add_u64 v[130:131], v[130:131], 0, s[54:55]
	s_mov_b32 m0, s16
	ds_read_b128 v[98:101], v81 offset:49152
	ds_read_b128 v[102:105], v81 offset:50176
	ds_read_b128 v[106:109], v81 offset:51200
	ds_read_b128 v[110:113], v81 offset:52224
	ds_read_b128 v[114:117], v81 offset:53248
	ds_read_b128 v[118:121], v81 offset:54272
	ds_read_b128 v[122:125], v81 offset:55296
	ds_read_b128 v[126:129], v81 offset:56320
	global_load_lds_dwordx4 v[130:131], off
	s_add_i32 m0, s16, 0x2000
	s_add_u32 s16, s20, 0x20080
	v_lshl_add_u64 v[130:131], v[132:133], 0, s[54:55]
	s_addc_u32 s17, s21, 0
	global_load_lds_dwordx4 v[130:131], off
	v_lshl_add_u64 v[130:131], s[16:17], 0, v[70:71]
	s_mov_b32 m0, s39
	s_nop 0
	global_load_lds_dwordx4 v[130:131], off
	v_lshl_add_u64 v[130:131], s[16:17], 0, v[66:67]
	s_mov_b32 m0, s40
	s_nop 0
	global_load_lds_dwordx4 v[130:131], off
	v_lshl_add_u64 v[130:131], v[134:135], 0, s[54:55]
	s_mov_b32 m0, s37
	s_nop 0
	global_load_lds_dwordx4 v[130:131], off
	v_lshl_add_u64 v[130:131], v[136:137], 0, s[54:55]
	s_mov_b32 m0, s38
	s_nop 0
	global_load_lds_dwordx4 v[130:131], off
	s_waitcnt vmcnt(8)
	s_waitcnt lgkmcnt(0)
	s_barrier
	s_setprio 1
	v_mfma_f32_16x16x32_bf16 v[30:33], v[82:85], v[98:101], v[30:33]
	v_mfma_f32_16x16x32_bf16 v[26:29], v[90:93], v[98:101], v[26:29]
	v_mfma_f32_16x16x32_bf16 v[22:25], v[82:85], v[106:109], v[22:25]
	v_mfma_f32_16x16x32_bf16 v[18:21], v[90:93], v[106:109], v[18:21]
	v_mfma_f32_16x16x32_bf16 v[14:17], v[82:85], v[114:117], v[14:17]
	v_mfma_f32_16x16x32_bf16 v[10:13], v[90:93], v[114:117], v[10:13]
	v_mfma_f32_16x16x32_bf16 v[6:9], v[82:85], v[122:125], v[6:9]
	v_mfma_f32_16x16x32_bf16 v[2:5], v[90:93], v[122:125], v[2:5]
	v_mfma_f32_16x16x32_bf16 v[30:33], v[86:89], v[102:105], v[30:33]
	v_mfma_f32_16x16x32_bf16 v[26:29], v[94:97], v[102:105], v[26:29]
	v_mfma_f32_16x16x32_bf16 v[22:25], v[86:89], v[110:113], v[22:25]
	v_mfma_f32_16x16x32_bf16 v[18:21], v[94:97], v[110:113], v[18:21]
	v_mfma_f32_16x16x32_bf16 v[14:17], v[86:89], v[118:121], v[14:17]
	v_mfma_f32_16x16x32_bf16 v[10:13], v[94:97], v[118:121], v[10:13]
	v_mfma_f32_16x16x32_bf16 v[6:9], v[86:89], v[126:129], v[6:9]
	v_mfma_f32_16x16x32_bf16 v[2:5], v[94:97], v[126:129], v[2:5]
	s_setprio 0
	s_setprio 1
	s_setprio 0
	s_barrier
	s_add_i32 s52, s52, 2
	s_add_u32 s46, s46, 0x100
	s_addc_u32 s47, s47, 0
	s_cmp_gt_u32 s52, 5
	s_mov_b64 s[16:17], s[18:19]
	s_cbranch_scc0 .LBB0_245
	s_and_b64 vcc, exec, s[6:7]
	s_cbranch_vccz .LBB0_248
	s_barrier

.LBB0_407:
	s_add_u32 s18, s16, 0x100
	s_addc_u32 s19, s17, 0
	s_add_i32 s47, 0, 0x10000
	s_cmp_eq_u32 s46, 6
	s_cselect_b32 s23, s13, s19
	s_cselect_b32 s22, s12, s18
	v_add_u32_e32 v0, s47, v201
	s_cselect_b32 s21, s15, s45
	s_cselect_b32 s20, s14, s3
	s_add_i32 s50, 0, 0x14000
	ds_read_b128 v[34:37], v0
	ds_read_b128 v[38:41], v0 offset:1024
	ds_read_b128 v[106:109], v0 offset:2048
	ds_read_b128 v[118:121], v0 offset:3072
	v_add_u32_e32 v0, s50, v201
	ds_read_b128 v[130:133], v0
	ds_read_b128 v[142:145], v0 offset:1024
	ds_read_b128 v[146:149], v0 offset:2048
	ds_read_b128 v[154:157], v0 offset:3072
	v_lshl_add_u64 v[198:199], s[16:17], 0, v[192:193]
	s_add_i32 m0, s31, 0xc000
	ds_read_b128 v[162:165], v204
	ds_read_b128 v[166:169], v204 offset:1024
	ds_read_b128 v[206:209], v204 offset:2048
	ds_read_b128 v[210:213], v204 offset:3072
	ds_read_b128 v[214:217], v204 offset:4096
	ds_read_b128 v[236:239], v204 offset:5120
	ds_read_b128 v[240:243], v204 offset:6144
	ds_read_b128 v[244:247], v204 offset:7168
	global_load_lds_dwordx4 v[198:199], off
	v_lshl_add_u64 v[198:199], s[16:17], 0, v[194:195]
	s_add_i32 m0, s31, 0xe000
	s_nop 0
	global_load_lds_dwordx4 v[198:199], off
	s_waitcnt vmcnt(8)
	s_waitcnt lgkmcnt(0)
	s_barrier
	s_setprio 1
	v_mfma_f32_16x16x32_bf16 v[158:161], v[34:37], v[162:165], v[158:161]
	v_mfma_f32_16x16x32_bf16 v[150:153], v[106:109], v[162:165], v[150:153]
	v_mfma_f32_16x16x32_bf16 v[126:129], v[34:37], v[206:209], v[126:129]
	v_mfma_f32_16x16x32_bf16 v[122:125], v[106:109], v[206:209], v[122:125]
	v_mfma_f32_16x16x32_bf16 v[102:105], v[34:37], v[214:217], v[102:105]
	v_mfma_f32_16x16x32_bf16 v[98:101], v[106:109], v[214:217], v[98:101]
	v_mfma_f32_16x16x32_bf16 v[86:89], v[34:37], v[240:243], v[86:89]
	v_mfma_f32_16x16x32_bf16 v[82:85], v[106:109], v[240:243], v[82:85]
	v_mfma_f32_16x16x32_bf16 v[158:161], v[38:41], v[166:169], v[158:161]
	v_mfma_f32_16x16x32_bf16 v[150:153], v[118:121], v[166:169], v[150:153]
	v_mfma_f32_16x16x32_bf16 v[126:129], v[38:41], v[210:213], v[126:129]
	v_mfma_f32_16x16x32_bf16 v[122:125], v[118:121], v[210:213], v[122:125]
	v_mfma_f32_16x16x32_bf16 v[102:105], v[38:41], v[236:239], v[102:105]
	v_mfma_f32_16x16x32_bf16 v[98:101], v[118:121], v[236:239], v[98:101]
	v_mfma_f32_16x16x32_bf16 v[86:89], v[38:41], v[244:247], v[86:89]
	v_mfma_f32_16x16x32_bf16 v[82:85], v[118:121], v[244:247], v[82:85]
	s_setprio 0
	s_setprio 1
	v_mfma_f32_16x16x32_bf16 v[138:141], v[130:133], v[162:165], v[138:141]
	v_mfma_f32_16x16x32_bf16 v[134:137], v[146:149], v[162:165], v[134:137]
	v_mfma_f32_16x16x32_bf16 v[114:117], v[130:133], v[206:209], v[114:117]
	v_mfma_f32_16x16x32_bf16 v[110:113], v[146:149], v[206:209], v[110:113]
	v_mfma_f32_16x16x32_bf16 v[94:97], v[130:133], v[214:217], v[94:97]
	v_mfma_f32_16x16x32_bf16 v[90:93], v[146:149], v[214:217], v[90:93]
	v_mfma_f32_16x16x32_bf16 v[78:81], v[130:133], v[240:243], v[78:81]
	v_mfma_f32_16x16x32_bf16 v[74:77], v[146:149], v[240:243], v[74:77]
	v_mfma_f32_16x16x32_bf16 v[138:141], v[142:145], v[166:169], v[138:141]
	v_mfma_f32_16x16x32_bf16 v[134:137], v[154:157], v[166:169], v[134:137]
	v_mfma_f32_16x16x32_bf16 v[114:117], v[142:145], v[210:213], v[114:117]
	v_mfma_f32_16x16x32_bf16 v[110:113], v[154:157], v[210:213], v[110:113]
	v_mfma_f32_16x16x32_bf16 v[94:97], v[142:145], v[236:239], v[94:97]
	v_mfma_f32_16x16x32_bf16 v[90:93], v[154:157], v[236:239], v[90:93]
	v_mfma_f32_16x16x32_bf16 v[78:81], v[142:145], v[244:247], v[78:81]
	v_mfma_f32_16x16x32_bf16 v[74:77], v[154:157], v[244:247], v[74:77]
	s_setprio 0
	s_barrier
	s_add_i32 s16, s47, s30
	v_lshl_add_u64 v[198:199], s[20:21], 0, v[184:185]
	s_mov_b32 m0, s16
	ds_read_b128 v[162:165], v204 offset:16384
	ds_read_b128 v[166:169], v204 offset:17408
	ds_read_b128 v[206:209], v204 offset:18432
	ds_read_b128 v[210:213], v204 offset:19456
	ds_read_b128 v[214:217], v204 offset:20480
	ds_read_b128 v[236:239], v204 offset:21504
	ds_read_b128 v[240:243], v204 offset:22528
	ds_read_b128 v[244:247], v204 offset:23552
	global_load_lds_dwordx4 v[198:199], off
	s_add_i32 m0, s16, 0x2000
	s_add_u32 s16, s20, 0x28000
	v_lshl_add_u64 v[218:219], s[20:21], 0, v[180:181]
	s_addc_u32 s17, s21, 0
	s_add_i32 s47, s50, s30
	global_load_lds_dwordx4 v[218:219], off
	v_lshl_add_u64 v[222:223], s[16:17], 0, v[184:185]
	s_mov_b32 m0, s47
	v_lshl_add_u64 v[232:233], s[22:23], 0, v[182:183]
	global_load_lds_dwordx4 v[222:223], off
	v_lshl_add_u64 v[222:223], s[16:17], 0, v[180:181]
	s_add_i32 m0, s47, 0x2000
	s_nop 0
	global_load_lds_dwordx4 v[222:223], off
	v_lshl_add_u64 v[222:223], s[22:23], 0, v[186:187]
	s_mov_b32 m0, s31
	s_nop 0
	global_load_lds_dwordx4 v[222:223], off
	s_mov_b32 m0, s34
	s_nop 0
	global_load_lds_dwordx4 v[232:233], off
	s_waitcnt vmcnt(8)
	s_waitcnt lgkmcnt(0)
	s_barrier
	s_setprio 1
	v_mfma_f32_16x16x32_bf16 v[70:73], v[34:37], v[162:165], v[70:73]
	v_mfma_f32_16x16x32_bf16 v[66:69], v[106:109], v[162:165], v[66:69]
	v_mfma_f32_16x16x32_bf16 v[54:57], v[34:37], v[206:209], v[54:57]
	v_mfma_f32_16x16x32_bf16 v[50:53], v[106:109], v[206:209], v[50:53]
	v_mfma_f32_16x16x32_bf16 v[30:33], v[34:37], v[214:217], v[30:33]
	v_mfma_f32_16x16x32_bf16 v[26:29], v[106:109], v[214:217], v[26:29]
	v_mfma_f32_16x16x32_bf16 v[14:17], v[34:37], v[240:243], v[14:17]
	v_mfma_f32_16x16x32_bf16 v[10:13], v[106:109], v[240:243], v[10:13]
	v_mfma_f32_16x16x32_bf16 v[70:73], v[38:41], v[166:169], v[70:73]
	v_mfma_f32_16x16x32_bf16 v[66:69], v[118:121], v[166:169], v[66:69]
	v_mfma_f32_16x16x32_bf16 v[54:57], v[38:41], v[210:213], v[54:57]
	v_mfma_f32_16x16x32_bf16 v[50:53], v[118:121], v[210:213], v[50:53]
	v_mfma_f32_16x16x32_bf16 v[30:33], v[38:41], v[236:239], v[30:33]
	v_mfma_f32_16x16x32_bf16 v[26:29], v[118:121], v[236:239], v[26:29]
	v_mfma_f32_16x16x32_bf16 v[14:17], v[38:41], v[244:247], v[14:17]
	v_mfma_f32_16x16x32_bf16 v[10:13], v[118:121], v[244:247], v[10:13]
	s_setprio 0
	s_setprio 1
	v_mfma_f32_16x16x32_bf16 v[46:49], v[130:133], v[206:209], v[46:49]
	v_mfma_f32_16x16x32_bf16 v[42:45], v[146:149], v[206:209], v[42:45]
	v_mfma_f32_16x16x32_bf16 v[22:25], v[130:133], v[214:217], v[22:25]
	v_mfma_f32_16x16x32_bf16 v[18:21], v[146:149], v[214:217], v[18:21]
	v_mfma_f32_16x16x32_bf16 v[6:9], v[130:133], v[240:243], v[6:9]
	v_mfma_f32_16x16x32_bf16 v[2:5], v[146:149], v[240:243], v[2:5]
	v_mfma_f32_16x16x32_bf16 v[34:37], v[130:133], v[162:165], v[62:65]
	v_mfma_f32_16x16x32_bf16 v[38:41], v[146:149], v[162:165], v[58:61]
	v_mfma_f32_16x16x32_bf16 v[46:49], v[142:145], v[210:213], v[46:49]
	v_mfma_f32_16x16x32_bf16 v[42:45], v[154:157], v[210:213], v[42:45]
	v_mfma_f32_16x16x32_bf16 v[22:25], v[142:145], v[236:239], v[22:25]
	v_mfma_f32_16x16x32_bf16 v[18:21], v[154:157], v[236:239], v[18:21]
	v_mfma_f32_16x16x32_bf16 v[6:9], v[142:145], v[244:247], v[6:9]
	v_mfma_f32_16x16x32_bf16 v[2:5], v[154:157], v[244:247], v[2:5]
	v_mfma_f32_16x16x32_bf16 v[34:37], v[142:145], v[166:169], v[34:37]
	v_mfma_f32_16x16x32_bf16 v[38:41], v[154:157], v[166:169], v[38:41]
	s_setprio 0
	s_barrier
	s_add_i32 s47, 0, 0x18000
	v_add_u32_e32 v0, s47, v201
	s_add_i32 s50, 0, 0x1c000
	ds_read_b128 v[58:61], v0
	ds_read_b128 v[62:65], v0 offset:1024
	ds_read_b128 v[106:109], v0 offset:2048
	ds_read_b128 v[118:121], v0 offset:3072
	v_add_u32_e32 v0, s50, v201
	ds_read_b128 v[130:133], v0
	ds_read_b128 v[142:145], v0 offset:1024
	ds_read_b128 v[146:149], v0 offset:2048
	ds_read_b128 v[154:157], v0 offset:3072
	s_add_u32 s16, s22, 0x28000
	s_addc_u32 s17, s23, 0
	s_mov_b32 m0, s35
	v_lshl_add_u64 v[248:249], s[16:17], 0, v[186:187]
	ds_read_b128 v[162:165], v204 offset:32768
	ds_read_b128 v[166:169], v204 offset:33792
	ds_read_b128 v[206:209], v204 offset:34816
	ds_read_b128 v[210:213], v204 offset:35840
	ds_read_b128 v[214:217], v204 offset:36864
	ds_read_b128 v[236:239], v204 offset:37888
	ds_read_b128 v[240:243], v204 offset:38912
	ds_read_b128 v[244:247], v204 offset:39936
	global_load_lds_dwordx4 v[248:249], off
	v_lshl_add_u64 v[248:249], s[16:17], 0, v[182:183]
	s_mov_b32 m0, s36
	s_nop 0
	global_load_lds_dwordx4 v[248:249], off
	s_waitcnt vmcnt(8)
	s_waitcnt lgkmcnt(0)
	s_barrier
	s_setprio 1
	v_mfma_f32_16x16x32_bf16 v[158:161], v[58:61], v[162:165], v[158:161]
	v_mfma_f32_16x16x32_bf16 v[150:153], v[106:109], v[162:165], v[150:153]
	v_mfma_f32_16x16x32_bf16 v[126:129], v[58:61], v[206:209], v[126:129]
	v_mfma_f32_16x16x32_bf16 v[122:125], v[106:109], v[206:209], v[122:125]
	v_mfma_f32_16x16x32_bf16 v[102:105], v[58:61], v[214:217], v[102:105]
	v_mfma_f32_16x16x32_bf16 v[98:101], v[106:109], v[214:217], v[98:101]
	v_mfma_f32_16x16x32_bf16 v[86:89], v[58:61], v[240:243], v[86:89]
	v_mfma_f32_16x16x32_bf16 v[82:85], v[106:109], v[240:243], v[82:85]
	v_mfma_f32_16x16x32_bf16 v[158:161], v[62:65], v[166:169], v[158:161]
	v_mfma_f32_16x16x32_bf16 v[150:153], v[118:121], v[166:169], v[150:153]
	v_mfma_f32_16x16x32_bf16 v[126:129], v[62:65], v[210:213], v[126:129]
	v_mfma_f32_16x16x32_bf16 v[122:125], v[118:121], v[210:213], v[122:125]
	v_mfma_f32_16x16x32_bf16 v[102:105], v[62:65], v[236:239], v[102:105]
	v_mfma_f32_16x16x32_bf16 v[98:101], v[118:121], v[236:239], v[98:101]
	v_mfma_f32_16x16x32_bf16 v[86:89], v[62:65], v[244:247], v[86:89]
	v_mfma_f32_16x16x32_bf16 v[82:85], v[118:121], v[244:247], v[82:85]
	s_setprio 0
	s_setprio 1
	v_mfma_f32_16x16x32_bf16 v[138:141], v[130:133], v[162:165], v[138:141]
	v_mfma_f32_16x16x32_bf16 v[134:137], v[146:149], v[162:165], v[134:137]
	v_mfma_f32_16x16x32_bf16 v[114:117], v[130:133], v[206:209], v[114:117]
	v_mfma_f32_16x16x32_bf16 v[110:113], v[146:149], v[206:209], v[110:113]
	v_mfma_f32_16x16x32_bf16 v[94:97], v[130:133], v[214:217], v[94:97]
	v_mfma_f32_16x16x32_bf16 v[90:93], v[146:149], v[214:217], v[90:93]
	v_mfma_f32_16x16x32_bf16 v[78:81], v[130:133], v[240:243], v[78:81]
	v_mfma_f32_16x16x32_bf16 v[74:77], v[146:149], v[240:243], v[74:77]
	v_mfma_f32_16x16x32_bf16 v[138:141], v[142:145], v[166:169], v[138:141]
	v_mfma_f32_16x16x32_bf16 v[134:137], v[154:157], v[166:169], v[134:137]
	v_mfma_f32_16x16x32_bf16 v[114:117], v[142:145], v[210:213], v[114:117]
	v_mfma_f32_16x16x32_bf16 v[110:113], v[154:157], v[210:213], v[110:113]
	v_mfma_f32_16x16x32_bf16 v[94:97], v[142:145], v[236:239], v[94:97]
	v_mfma_f32_16x16x32_bf16 v[90:93], v[154:157], v[236:239], v[90:93]
	v_mfma_f32_16x16x32_bf16 v[78:81], v[142:145], v[244:247], v[78:81]
	v_mfma_f32_16x16x32_bf16 v[74:77], v[154:157], v[244:247], v[74:77]
	s_setprio 0
	s_barrier
	s_add_i32 s16, s47, s30
	v_lshl_add_u64 v[198:199], v[198:199], 0, s[54:55]
	s_mov_b32 m0, s16
	ds_read_b128 v[162:165], v204 offset:49152
	ds_read_b128 v[166:169], v204 offset:50176
	ds_read_b128 v[206:209], v204 offset:51200
	ds_read_b128 v[210:213], v204 offset:52224
	ds_read_b128 v[214:217], v204 offset:53248
	ds_read_b128 v[236:239], v204 offset:54272
	ds_read_b128 v[240:243], v204 offset:55296
	ds_read_b128 v[244:247], v204 offset:56320
	global_load_lds_dwordx4 v[198:199], off
	s_add_i32 m0, s16, 0x2000
	s_add_u32 s16, s20, 0x28080
	v_lshl_add_u64 v[198:199], v[218:219], 0, s[54:55]
	s_addc_u32 s17, s21, 0
	s_add_i32 s20, s50, s30
	global_load_lds_dwordx4 v[198:199], off
	v_lshl_add_u64 v[198:199], s[16:17], 0, v[184:185]
	s_mov_b32 m0, s20
	s_nop 0
	global_load_lds_dwordx4 v[198:199], off
	v_lshl_add_u64 v[198:199], s[16:17], 0, v[180:181]
	s_add_i32 m0, s20, 0x2000
	s_nop 0
	global_load_lds_dwordx4 v[198:199], off
	v_lshl_add_u64 v[198:199], v[222:223], 0, s[54:55]
	s_mov_b32 m0, s38
	s_nop 0
	global_load_lds_dwordx4 v[198:199], off
	v_lshl_add_u64 v[198:199], v[232:233], 0, s[54:55]
	s_mov_b32 m0, s39
	s_nop 0
	global_load_lds_dwordx4 v[198:199], off
	s_waitcnt vmcnt(8)
	s_waitcnt lgkmcnt(0)
	s_barrier
	s_setprio 1
	v_mfma_f32_16x16x32_bf16 v[70:73], v[58:61], v[162:165], v[70:73]
	v_mfma_f32_16x16x32_bf16 v[66:69], v[106:109], v[162:165], v[66:69]
	v_mfma_f32_16x16x32_bf16 v[54:57], v[58:61], v[206:209], v[54:57]
	v_mfma_f32_16x16x32_bf16 v[50:53], v[106:109], v[206:209], v[50:53]
	v_mfma_f32_16x16x32_bf16 v[30:33], v[58:61], v[214:217], v[30:33]
	v_mfma_f32_16x16x32_bf16 v[26:29], v[106:109], v[214:217], v[26:29]
	v_mfma_f32_16x16x32_bf16 v[14:17], v[58:61], v[240:243], v[14:17]
	v_mfma_f32_16x16x32_bf16 v[10:13], v[106:109], v[240:243], v[10:13]
	v_mfma_f32_16x16x32_bf16 v[70:73], v[62:65], v[166:169], v[70:73]
	v_mfma_f32_16x16x32_bf16 v[66:69], v[118:121], v[166:169], v[66:69]
	v_mfma_f32_16x16x32_bf16 v[54:57], v[62:65], v[210:213], v[54:57]
	v_mfma_f32_16x16x32_bf16 v[50:53], v[118:121], v[210:213], v[50:53]
	v_mfma_f32_16x16x32_bf16 v[30:33], v[62:65], v[236:239], v[30:33]
	v_mfma_f32_16x16x32_bf16 v[26:29], v[118:121], v[236:239], v[26:29]
	v_mfma_f32_16x16x32_bf16 v[14:17], v[62:65], v[244:247], v[14:17]
	v_mfma_f32_16x16x32_bf16 v[10:13], v[118:121], v[244:247], v[10:13]
	s_setprio 0
	s_setprio 1
	v_mfma_f32_16x16x32_bf16 v[34:37], v[130:133], v[162:165], v[34:37]
	v_mfma_f32_16x16x32_bf16 v[62:65], v[142:145], v[166:169], v[34:37]
	v_mfma_f32_16x16x32_bf16 v[34:37], v[146:149], v[162:165], v[38:41]
	v_mfma_f32_16x16x32_bf16 v[58:61], v[154:157], v[166:169], v[34:37]
	v_mfma_f32_16x16x32_bf16 v[34:37], v[130:133], v[206:209], v[46:49]
	v_mfma_f32_16x16x32_bf16 v[46:49], v[142:145], v[210:213], v[34:37]
	v_mfma_f32_16x16x32_bf16 v[34:37], v[146:149], v[206:209], v[42:45]
	v_mfma_f32_16x16x32_bf16 v[22:25], v[130:133], v[214:217], v[22:25]
	v_mfma_f32_16x16x32_bf16 v[18:21], v[146:149], v[214:217], v[18:21]
	v_mfma_f32_16x16x32_bf16 v[6:9], v[130:133], v[240:243], v[6:9]
	v_mfma_f32_16x16x32_bf16 v[2:5], v[146:149], v[240:243], v[2:5]
	v_mfma_f32_16x16x32_bf16 v[42:45], v[154:157], v[210:213], v[34:37]
	v_mfma_f32_16x16x32_bf16 v[22:25], v[142:145], v[236:239], v[22:25]
	v_mfma_f32_16x16x32_bf16 v[18:21], v[154:157], v[236:239], v[18:21]
	v_mfma_f32_16x16x32_bf16 v[6:9], v[142:145], v[244:247], v[6:9]
	v_mfma_f32_16x16x32_bf16 v[2:5], v[154:157], v[244:247], v[2:5]
	s_setprio 0
	s_barrier
	s_add_i32 s46, s46, 2
	s_add_u32 s3, s3, 0x100
	s_addc_u32 s45, s45, 0
	s_cmp_gt_u32 s46, 7
	s_mov_b64 s[16:17], s[18:19]
	s_cbranch_scc0 .LBB0_407
	s_and_b64 vcc, exec, s[10:11]
	s_cbranch_vccz .LBB0_410
	s_barrier

.LBB0_501:
	s_add_u32 s30, s28, 0xfffc0080
	s_addc_u32 s31, s29, -1
	s_add_i32 s53, 0, 0x10000
	s_cmp_eq_u32 s50, 12
	s_cselect_b32 s35, s2, s31
	s_cselect_b32 s34, s3, s30
	s_cselect_b32 s31, s17, s27
	s_cselect_b32 s30, s19, s25
	s_add_i32 s60, 0, 0x14000
	v_add_u32_e32 v142, s53, v236
	v_add_u32_e32 v158, s60, v236
	ds_read_b128 v[114:117], v142
	ds_read_b128 v[122:125], v142 offset:1024
	ds_read_b128 v[130:133], v142 offset:2048
	ds_read_b128 v[142:145], v142 offset:3072
	ds_read_b128 v[146:149], v158
	ds_read_b128 v[150:153], v158 offset:1024
	ds_read_b128 v[154:157], v158 offset:2048
	ds_read_b128 v[158:161], v158 offset:3072
	v_lshl_add_u64 v[216:217], s[28:29], 0, v[180:181]
	s_add_i32 m0, s43, 0xc000
	ds_read_b128 v[184:187], v238
	ds_read_b128 v[188:191], v238 offset:1024
	ds_read_b128 v[192:195], v238 offset:2048
	ds_read_b128 v[196:199], v238 offset:3072
	ds_read_b128 v[200:203], v238 offset:4096
	ds_read_b128 v[204:207], v238 offset:5120
	ds_read_b128 v[208:211], v238 offset:6144
	ds_read_b128 v[212:215], v238 offset:7168
	global_load_lds_dwordx4 v[216:217], off
	v_lshl_add_u64 v[216:217], s[28:29], 0, v[182:183]
	s_add_i32 m0, s43, 0xe000
	s_nop 0
	global_load_lds_dwordx4 v[216:217], off
	s_waitcnt vmcnt(8)
	s_waitcnt lgkmcnt(0)
	s_barrier
	s_setprio 1
	v_mfma_f32_16x16x32_bf16 v[138:141], v[114:117], v[184:187], v[138:141]
	v_mfma_f32_16x16x32_bf16 v[118:121], v[130:133], v[184:187], v[118:121]
	v_mfma_f32_16x16x32_bf16 v[110:113], v[114:117], v[192:195], v[110:113]
	v_mfma_f32_16x16x32_bf16 v[102:105], v[130:133], v[192:195], v[102:105]
	v_mfma_f32_16x16x32_bf16 v[94:97], v[114:117], v[200:203], v[94:97]
	v_mfma_f32_16x16x32_bf16 v[86:89], v[130:133], v[200:203], v[86:89]
	v_mfma_f32_16x16x32_bf16 v[78:81], v[114:117], v[208:211], v[78:81]
	v_mfma_f32_16x16x32_bf16 v[70:73], v[130:133], v[208:211], v[70:73]
	v_mfma_f32_16x16x32_bf16 v[138:141], v[122:125], v[188:191], v[138:141]
	v_mfma_f32_16x16x32_bf16 v[118:121], v[142:145], v[188:191], v[118:121]
	v_mfma_f32_16x16x32_bf16 v[110:113], v[122:125], v[196:199], v[110:113]
	v_mfma_f32_16x16x32_bf16 v[102:105], v[142:145], v[196:199], v[102:105]
	v_mfma_f32_16x16x32_bf16 v[94:97], v[122:125], v[204:207], v[94:97]
	v_mfma_f32_16x16x32_bf16 v[86:89], v[142:145], v[204:207], v[86:89]
	v_mfma_f32_16x16x32_bf16 v[78:81], v[122:125], v[212:215], v[78:81]
	v_mfma_f32_16x16x32_bf16 v[70:73], v[142:145], v[212:215], v[70:73]
	s_setprio 0
	s_setprio 1
	v_mfma_f32_16x16x32_bf16 v[134:137], v[146:149], v[184:187], v[134:137]
	v_mfma_f32_16x16x32_bf16 v[126:129], v[154:157], v[184:187], v[126:129]
	v_mfma_f32_16x16x32_bf16 v[106:109], v[146:149], v[192:195], v[106:109]
	v_mfma_f32_16x16x32_bf16 v[98:101], v[154:157], v[192:195], v[98:101]
	v_mfma_f32_16x16x32_bf16 v[90:93], v[146:149], v[200:203], v[90:93]
	v_mfma_f32_16x16x32_bf16 v[82:85], v[154:157], v[200:203], v[82:85]
	v_mfma_f32_16x16x32_bf16 v[74:77], v[146:149], v[208:211], v[74:77]
	v_mfma_f32_16x16x32_bf16 v[66:69], v[154:157], v[208:211], v[66:69]
	v_mfma_f32_16x16x32_bf16 v[134:137], v[150:153], v[188:191], v[134:137]
	v_mfma_f32_16x16x32_bf16 v[126:129], v[158:161], v[188:191], v[126:129]
	v_mfma_f32_16x16x32_bf16 v[106:109], v[150:153], v[196:199], v[106:109]
	v_mfma_f32_16x16x32_bf16 v[98:101], v[158:161], v[196:199], v[98:101]
	v_mfma_f32_16x16x32_bf16 v[90:93], v[150:153], v[204:207], v[90:93]
	v_mfma_f32_16x16x32_bf16 v[82:85], v[158:161], v[204:207], v[82:85]
	v_mfma_f32_16x16x32_bf16 v[74:77], v[150:153], v[212:215], v[74:77]
	v_mfma_f32_16x16x32_bf16 v[66:69], v[158:161], v[212:215], v[66:69]
	s_setprio 0
	s_barrier
	s_add_i32 s53, s53, s42
	v_lshl_add_u64 v[216:217], s[30:31], 0, v[0:1]
	s_mov_b32 m0, s53
	ds_read_b128 v[184:187], v238 offset:16384
	ds_read_b128 v[188:191], v238 offset:17408
	ds_read_b128 v[192:195], v238 offset:18432
	ds_read_b128 v[196:199], v238 offset:19456
	ds_read_b128 v[200:203], v238 offset:20480
	ds_read_b128 v[204:207], v238 offset:21504
	ds_read_b128 v[208:211], v238 offset:22528
	ds_read_b128 v[212:215], v238 offset:23552
	global_load_lds_dwordx4 v[216:217], off
	s_add_i32 m0, s53, 0x2000
	s_add_u32 s64, s30, 0x40000
	v_lshl_add_u64 v[218:219], s[30:31], 0, v[166:167]
	s_addc_u32 s65, s31, 0
	s_add_i32 s53, s60, s42
	global_load_lds_dwordx4 v[218:219], off
	v_lshl_add_u64 v[222:223], s[64:65], 0, v[0:1]
	s_mov_b32 m0, s53
	v_lshl_add_u64 v[232:233], s[34:35], 0, v[164:165]
	global_load_lds_dwordx4 v[222:223], off
	v_lshl_add_u64 v[222:223], s[64:65], 0, v[166:167]
	s_add_i32 m0, s53, 0x2000
	s_nop 0
	global_load_lds_dwordx4 v[222:223], off
	v_lshl_add_u64 v[222:223], s[34:35], 0, v[162:163]
	s_mov_b32 m0, s43
	s_nop 0
	global_load_lds_dwordx4 v[222:223], off
	s_mov_b32 m0, s45
	s_nop 0
	global_load_lds_dwordx4 v[232:233], off
	s_waitcnt vmcnt(8)
	s_waitcnt lgkmcnt(0)
	s_barrier
	s_setprio 1
	v_mfma_f32_16x16x32_bf16 v[62:65], v[114:117], v[184:187], v[62:65]
	v_mfma_f32_16x16x32_bf16 v[54:57], v[130:133], v[184:187], v[54:57]
	v_mfma_f32_16x16x32_bf16 v[46:49], v[114:117], v[192:195], v[46:49]
	v_mfma_f32_16x16x32_bf16 v[38:41], v[130:133], v[192:195], v[38:41]
	v_mfma_f32_16x16x32_bf16 v[30:33], v[114:117], v[200:203], v[30:33]
	v_mfma_f32_16x16x32_bf16 v[22:25], v[130:133], v[200:203], v[22:25]
	v_mfma_f32_16x16x32_bf16 v[14:17], v[114:117], v[208:211], v[14:17]
	v_mfma_f32_16x16x32_bf16 v[6:9], v[130:133], v[208:211], v[6:9]
	v_mfma_f32_16x16x32_bf16 v[62:65], v[122:125], v[188:191], v[62:65]
	v_mfma_f32_16x16x32_bf16 v[54:57], v[142:145], v[188:191], v[54:57]
	v_mfma_f32_16x16x32_bf16 v[46:49], v[122:125], v[196:199], v[46:49]
	v_mfma_f32_16x16x32_bf16 v[38:41], v[142:145], v[196:199], v[38:41]
	v_mfma_f32_16x16x32_bf16 v[30:33], v[122:125], v[204:207], v[30:33]
	v_mfma_f32_16x16x32_bf16 v[22:25], v[142:145], v[204:207], v[22:25]
	v_mfma_f32_16x16x32_bf16 v[14:17], v[122:125], v[212:215], v[14:17]
	v_mfma_f32_16x16x32_bf16 v[6:9], v[142:145], v[212:215], v[6:9]
	s_setprio 0
	s_setprio 1
	v_mfma_f32_16x16x32_bf16 v[58:61], v[146:149], v[184:187], v[58:61]
	v_mfma_f32_16x16x32_bf16 v[50:53], v[154:157], v[184:187], v[50:53]
	v_mfma_f32_16x16x32_bf16 v[42:45], v[146:149], v[192:195], v[42:45]
	v_mfma_f32_16x16x32_bf16 v[34:37], v[154:157], v[192:195], v[34:37]
	v_mfma_f32_16x16x32_bf16 v[26:29], v[146:149], v[200:203], v[26:29]
	v_mfma_f32_16x16x32_bf16 v[18:21], v[154:157], v[200:203], v[18:21]
	v_mfma_f32_16x16x32_bf16 v[10:13], v[146:149], v[208:211], v[10:13]
	v_mfma_f32_16x16x32_bf16 v[2:5], v[154:157], v[208:211], v[2:5]
	v_mfma_f32_16x16x32_bf16 v[58:61], v[150:153], v[188:191], v[58:61]
	v_mfma_f32_16x16x32_bf16 v[50:53], v[158:161], v[188:191], v[50:53]
	v_mfma_f32_16x16x32_bf16 v[42:45], v[150:153], v[196:199], v[42:45]
	v_mfma_f32_16x16x32_bf16 v[34:37], v[158:161], v[196:199], v[34:37]
	v_mfma_f32_16x16x32_bf16 v[26:29], v[150:153], v[204:207], v[26:29]
	v_mfma_f32_16x16x32_bf16 v[18:21], v[158:161], v[204:207], v[18:21]
	v_mfma_f32_16x16x32_bf16 v[10:13], v[150:153], v[212:215], v[10:13]
	v_mfma_f32_16x16x32_bf16 v[2:5], v[158:161], v[212:215], v[2:5]
	s_setprio 0
	s_barrier
	s_add_i32 s53, 0, 0x18000
	s_add_i32 s60, 0, 0x1c000
	v_add_u32_e32 v142, s53, v236
	v_add_u32_e32 v158, s60, v236
	ds_read_b128 v[114:117], v142
	ds_read_b128 v[122:125], v142 offset:1024
	ds_read_b128 v[130:133], v142 offset:2048
	ds_read_b128 v[142:145], v142 offset:3072
	ds_read_b128 v[146:149], v158
	ds_read_b128 v[150:153], v158 offset:1024
	ds_read_b128 v[154:157], v158 offset:2048
	ds_read_b128 v[158:161], v158 offset:3072
	s_add_u32 s34, s34, 0x40000
	s_addc_u32 s35, s35, 0
	s_mov_b32 m0, s46
	v_lshl_add_u64 v[240:241], s[34:35], 0, v[162:163]
	ds_read_b128 v[184:187], v238 offset:32768
	ds_read_b128 v[188:191], v238 offset:33792
	ds_read_b128 v[192:195], v238 offset:34816
	ds_read_b128 v[196:199], v238 offset:35840
	ds_read_b128 v[200:203], v238 offset:36864
	ds_read_b128 v[204:207], v238 offset:37888
	ds_read_b128 v[208:211], v238 offset:38912
	ds_read_b128 v[212:215], v238 offset:39936
	global_load_lds_dwordx4 v[240:241], off
	v_lshl_add_u64 v[240:241], s[34:35], 0, v[164:165]
	s_mov_b32 m0, s47
	s_nop 0
	global_load_lds_dwordx4 v[240:241], off
	s_waitcnt vmcnt(8)
	s_waitcnt lgkmcnt(0)
	s_barrier
	s_setprio 1
	v_mfma_f32_16x16x32_bf16 v[138:141], v[114:117], v[184:187], v[138:141]
	v_mfma_f32_16x16x32_bf16 v[118:121], v[130:133], v[184:187], v[118:121]
	v_mfma_f32_16x16x32_bf16 v[110:113], v[114:117], v[192:195], v[110:113]
	v_mfma_f32_16x16x32_bf16 v[102:105], v[130:133], v[192:195], v[102:105]
	v_mfma_f32_16x16x32_bf16 v[94:97], v[114:117], v[200:203], v[94:97]
	v_mfma_f32_16x16x32_bf16 v[86:89], v[130:133], v[200:203], v[86:89]
	v_mfma_f32_16x16x32_bf16 v[78:81], v[114:117], v[208:211], v[78:81]
	v_mfma_f32_16x16x32_bf16 v[70:73], v[130:133], v[208:211], v[70:73]
	v_mfma_f32_16x16x32_bf16 v[138:141], v[122:125], v[188:191], v[138:141]
	v_mfma_f32_16x16x32_bf16 v[118:121], v[142:145], v[188:191], v[118:121]
	v_mfma_f32_16x16x32_bf16 v[110:113], v[122:125], v[196:199], v[110:113]
	v_mfma_f32_16x16x32_bf16 v[102:105], v[142:145], v[196:199], v[102:105]
	v_mfma_f32_16x16x32_bf16 v[94:97], v[122:125], v[204:207], v[94:97]
	v_mfma_f32_16x16x32_bf16 v[86:89], v[142:145], v[204:207], v[86:89]
	v_mfma_f32_16x16x32_bf16 v[78:81], v[122:125], v[212:215], v[78:81]
	v_mfma_f32_16x16x32_bf16 v[70:73], v[142:145], v[212:215], v[70:73]
	s_setprio 0
	s_setprio 1
	v_mfma_f32_16x16x32_bf16 v[134:137], v[146:149], v[184:187], v[134:137]
	v_mfma_f32_16x16x32_bf16 v[126:129], v[154:157], v[184:187], v[126:129]
	v_mfma_f32_16x16x32_bf16 v[106:109], v[146:149], v[192:195], v[106:109]
	v_mfma_f32_16x16x32_bf16 v[98:101], v[154:157], v[192:195], v[98:101]
	v_mfma_f32_16x16x32_bf16 v[90:93], v[146:149], v[200:203], v[90:93]
	v_mfma_f32_16x16x32_bf16 v[82:85], v[154:157], v[200:203], v[82:85]
	v_mfma_f32_16x16x32_bf16 v[74:77], v[146:149], v[208:211], v[74:77]
	v_mfma_f32_16x16x32_bf16 v[66:69], v[154:157], v[208:211], v[66:69]
	v_mfma_f32_16x16x32_bf16 v[134:137], v[150:153], v[188:191], v[134:137]
	v_mfma_f32_16x16x32_bf16 v[126:129], v[158:161], v[188:191], v[126:129]
	v_mfma_f32_16x16x32_bf16 v[106:109], v[150:153], v[196:199], v[106:109]
	v_mfma_f32_16x16x32_bf16 v[98:101], v[158:161], v[196:199], v[98:101]
	v_mfma_f32_16x16x32_bf16 v[90:93], v[150:153], v[204:207], v[90:93]
	v_mfma_f32_16x16x32_bf16 v[82:85], v[158:161], v[204:207], v[82:85]
	v_mfma_f32_16x16x32_bf16 v[74:77], v[150:153], v[212:215], v[74:77]
	v_mfma_f32_16x16x32_bf16 v[66:69], v[158:161], v[212:215], v[66:69]
	s_setprio 0
	s_barrier
	s_add_i32 s34, s53, s42
	v_lshl_add_u64 v[216:217], v[216:217], 0, s[54:55]
	s_mov_b32 m0, s34
	ds_read_b128 v[184:187], v238 offset:49152
	ds_read_b128 v[188:191], v238 offset:50176
	ds_read_b128 v[192:195], v238 offset:51200
	ds_read_b128 v[196:199], v238 offset:52224
	ds_read_b128 v[200:203], v238 offset:53248
	ds_read_b128 v[204:207], v238 offset:54272
	ds_read_b128 v[208:211], v238 offset:55296
	ds_read_b128 v[212:215], v238 offset:56320
	global_load_lds_dwordx4 v[216:217], off
	s_add_i32 m0, s34, 0x2000
	s_add_u32 s30, s30, 0x40080
	v_lshl_add_u64 v[216:217], v[218:219], 0, s[54:55]
	s_addc_u32 s31, s31, 0
	s_add_i32 s34, s60, s42
	global_load_lds_dwordx4 v[216:217], off
	v_lshl_add_u64 v[216:217], s[30:31], 0, v[0:1]
	s_mov_b32 m0, s34
	s_nop 0
	global_load_lds_dwordx4 v[216:217], off
	v_lshl_add_u64 v[216:217], s[30:31], 0, v[166:167]
	s_add_i32 m0, s34, 0x2000
	s_nop 0
	global_load_lds_dwordx4 v[216:217], off
	v_lshl_add_u64 v[216:217], v[222:223], 0, s[54:55]
	s_mov_b32 m0, s56
	s_nop 0
	global_load_lds_dwordx4 v[216:217], off
	v_lshl_add_u64 v[216:217], v[232:233], 0, s[54:55]
	s_mov_b32 m0, s57
	s_nop 0
	global_load_lds_dwordx4 v[216:217], off
	s_waitcnt vmcnt(8)
	s_waitcnt lgkmcnt(0)
	s_barrier
	s_setprio 1
	v_mfma_f32_16x16x32_bf16 v[62:65], v[114:117], v[184:187], v[62:65]
	v_mfma_f32_16x16x32_bf16 v[54:57], v[130:133], v[184:187], v[54:57]
	v_mfma_f32_16x16x32_bf16 v[46:49], v[114:117], v[192:195], v[46:49]
	v_mfma_f32_16x16x32_bf16 v[38:41], v[130:133], v[192:195], v[38:41]
	v_mfma_f32_16x16x32_bf16 v[30:33], v[114:117], v[200:203], v[30:33]
	v_mfma_f32_16x16x32_bf16 v[22:25], v[130:133], v[200:203], v[22:25]
	v_mfma_f32_16x16x32_bf16 v[14:17], v[114:117], v[208:211], v[14:17]
	v_mfma_f32_16x16x32_bf16 v[6:9], v[130:133], v[208:211], v[6:9]
	v_mfma_f32_16x16x32_bf16 v[62:65], v[122:125], v[188:191], v[62:65]
	v_mfma_f32_16x16x32_bf16 v[54:57], v[142:145], v[188:191], v[54:57]
	v_mfma_f32_16x16x32_bf16 v[46:49], v[122:125], v[196:199], v[46:49]
	v_mfma_f32_16x16x32_bf16 v[38:41], v[142:145], v[196:199], v[38:41]
	v_mfma_f32_16x16x32_bf16 v[30:33], v[122:125], v[204:207], v[30:33]
	v_mfma_f32_16x16x32_bf16 v[22:25], v[142:145], v[204:207], v[22:25]
	v_mfma_f32_16x16x32_bf16 v[14:17], v[122:125], v[212:215], v[14:17]
	v_mfma_f32_16x16x32_bf16 v[6:9], v[142:145], v[212:215], v[6:9]
	s_setprio 0
	s_setprio 1
	v_mfma_f32_16x16x32_bf16 v[58:61], v[146:149], v[184:187], v[58:61]
	v_mfma_f32_16x16x32_bf16 v[50:53], v[154:157], v[184:187], v[50:53]
	v_mfma_f32_16x16x32_bf16 v[42:45], v[146:149], v[192:195], v[42:45]
	v_mfma_f32_16x16x32_bf16 v[34:37], v[154:157], v[192:195], v[34:37]
	v_mfma_f32_16x16x32_bf16 v[26:29], v[146:149], v[200:203], v[26:29]
	v_mfma_f32_16x16x32_bf16 v[18:21], v[154:157], v[200:203], v[18:21]
	v_mfma_f32_16x16x32_bf16 v[10:13], v[146:149], v[208:211], v[10:13]
	v_mfma_f32_16x16x32_bf16 v[2:5], v[154:157], v[208:211], v[2:5]
	v_mfma_f32_16x16x32_bf16 v[58:61], v[150:153], v[188:191], v[58:61]
	v_mfma_f32_16x16x32_bf16 v[50:53], v[158:161], v[188:191], v[50:53]
	v_mfma_f32_16x16x32_bf16 v[42:45], v[150:153], v[196:199], v[42:45]
	v_mfma_f32_16x16x32_bf16 v[34:37], v[158:161], v[196:199], v[34:37]
	v_mfma_f32_16x16x32_bf16 v[26:29], v[150:153], v[204:207], v[26:29]
	v_mfma_f32_16x16x32_bf16 v[18:21], v[158:161], v[204:207], v[18:21]
	v_mfma_f32_16x16x32_bf16 v[10:13], v[150:153], v[212:215], v[10:13]
	v_mfma_f32_16x16x32_bf16 v[2:5], v[158:161], v[212:215], v[2:5]
	s_setprio 0
	s_barrier
	s_add_i32 s50, s50, 2
	s_add_u32 s28, s28, 0x100
	s_addc_u32 s29, s29, 0
	s_add_u32 s25, s25, 0x100
	s_addc_u32 s27, s27, 0
	s_cmp_gt_u32 s50, 13
	s_cbranch_scc0 .LBB0_501
	s_and_b64 vcc, exec, s[14:15]
	s_cbranch_vccz .LBB0_504
	s_barrier

.LBB0_613:
	s_add_u32 s38, s8, 0xfffc0080
	s_addc_u32 s39, s9, -1
	s_add_i32 s53, 0, 0x10000
	s_cmp_eq_u32 s43, 12
	s_cselect_b32 s41, s2, s39
	s_cselect_b32 s40, s3, s38
	v_add_u32_e32 v0, s53, v182
	s_cselect_b32 s39, s11, s42
	s_cselect_b32 s38, s27, s29
	s_add_i32 s60, 0, 0x14000
	ds_read_b128 v[106:109], v0
	ds_read_b128 v[110:113], v0 offset:1024
	ds_read_b128 v[114:117], v0 offset:2048
	ds_read_b128 v[118:121], v0 offset:3072
	v_add_u32_e32 v0, s60, v182
	ds_read_b128 v[160:163], v0
	ds_read_b128 v[164:167], v0 offset:1024
	ds_read_b128 v[194:197], v0 offset:2048
	ds_read_b128 v[198:201], v0 offset:3072
	v_lshl_add_u64 v[168:169], s[8:9], 0, v[154:155]
	s_add_i32 m0, s37, 0xc000
	ds_read_b128 v[202:205], v192
	ds_read_b128 v[206:209], v192 offset:1024
	ds_read_b128 v[210:213], v192 offset:2048
	ds_read_b128 v[214:217], v192 offset:3072
	ds_read_b128 v[236:239], v192 offset:4096
	ds_read_b128 v[240:243], v192 offset:5120
	ds_read_b128 v[244:247], v192 offset:6144
	ds_read_b128 v[248:251], v192 offset:7168
	global_load_lds_dwordx4 v[168:169], off
	v_lshl_add_u64 v[168:169], s[8:9], 0, v[156:157]
	s_add_i32 m0, s37, 0xe000
	s_nop 0
	global_load_lds_dwordx4 v[168:169], off
	s_waitcnt vmcnt(8)
	s_waitcnt lgkmcnt(0)
	s_barrier
	s_setprio 1
	v_mfma_f32_16x16x32_bf16 v[70:73], v[106:109], v[202:205], v[70:73]
	v_mfma_f32_16x16x32_bf16 v[66:69], v[114:117], v[202:205], v[66:69]
	v_mfma_f32_16x16x32_bf16 v[54:57], v[106:109], v[210:213], v[54:57]
	v_mfma_f32_16x16x32_bf16 v[50:53], v[114:117], v[210:213], v[50:53]
	v_mfma_f32_16x16x32_bf16 v[46:49], v[106:109], v[236:239], v[46:49]
	v_mfma_f32_16x16x32_bf16 v[42:45], v[114:117], v[236:239], v[42:45]
	v_mfma_f32_16x16x32_bf16 v[38:41], v[106:109], v[244:247], v[38:41]
	v_mfma_f32_16x16x32_bf16 v[34:37], v[114:117], v[244:247], v[34:37]
	v_mfma_f32_16x16x32_bf16 v[70:73], v[110:113], v[206:209], v[70:73]
	v_mfma_f32_16x16x32_bf16 v[66:69], v[118:121], v[206:209], v[66:69]
	v_mfma_f32_16x16x32_bf16 v[54:57], v[110:113], v[214:217], v[54:57]
	v_mfma_f32_16x16x32_bf16 v[50:53], v[118:121], v[214:217], v[50:53]
	v_mfma_f32_16x16x32_bf16 v[46:49], v[110:113], v[240:243], v[46:49]
	v_mfma_f32_16x16x32_bf16 v[42:45], v[118:121], v[240:243], v[42:45]
	v_mfma_f32_16x16x32_bf16 v[38:41], v[110:113], v[248:251], v[38:41]
	v_mfma_f32_16x16x32_bf16 v[34:37], v[118:121], v[248:251], v[34:37]
	s_setprio 0
	s_setprio 1
	v_mfma_f32_16x16x32_bf16 v[142:145], v[160:163], v[202:205], v[142:145]
	v_mfma_f32_16x16x32_bf16 v[138:141], v[194:197], v[202:205], v[138:141]
	v_mfma_f32_16x16x32_bf16 v[134:137], v[160:163], v[210:213], v[134:137]
	v_mfma_f32_16x16x32_bf16 v[130:133], v[194:197], v[210:213], v[130:133]
	v_mfma_f32_16x16x32_bf16 v[126:129], v[160:163], v[236:239], v[126:129]
	v_mfma_f32_16x16x32_bf16 v[122:125], v[194:197], v[236:239], v[122:125]
	v_mfma_f32_16x16x32_bf16 v[102:105], v[160:163], v[244:247], v[102:105]
	v_mfma_f32_16x16x32_bf16 v[98:101], v[194:197], v[244:247], v[98:101]
	v_mfma_f32_16x16x32_bf16 v[142:145], v[164:167], v[206:209], v[142:145]
	v_mfma_f32_16x16x32_bf16 v[138:141], v[198:201], v[206:209], v[138:141]
	v_mfma_f32_16x16x32_bf16 v[134:137], v[164:167], v[214:217], v[134:137]
	v_mfma_f32_16x16x32_bf16 v[130:133], v[198:201], v[214:217], v[130:133]
	v_mfma_f32_16x16x32_bf16 v[126:129], v[164:167], v[240:243], v[126:129]
	v_mfma_f32_16x16x32_bf16 v[122:125], v[198:201], v[240:243], v[122:125]
	v_mfma_f32_16x16x32_bf16 v[102:105], v[164:167], v[248:251], v[102:105]
	v_mfma_f32_16x16x32_bf16 v[98:101], v[198:201], v[248:251], v[98:101]
	s_setprio 0
	s_barrier
	s_add_i32 s53, s53, s57
	v_lshl_add_u64 v[168:169], s[38:39], 0, v[148:149]
	s_mov_b32 m0, s53
	ds_read_b128 v[202:205], v192 offset:16384
	ds_read_b128 v[206:209], v192 offset:17408
	ds_read_b128 v[210:213], v192 offset:18432
	ds_read_b128 v[214:217], v192 offset:19456
	ds_read_b128 v[236:239], v192 offset:20480
	ds_read_b128 v[240:243], v192 offset:21504
	ds_read_b128 v[244:247], v192 offset:22528
	ds_read_b128 v[248:251], v192 offset:23552
	global_load_lds_dwordx4 v[168:169], off
	s_add_i32 m0, s53, 0x2000
	s_add_u32 s64, s38, 0x40000
	v_lshl_add_u64 v[218:219], s[38:39], 0, v[152:153]
	s_addc_u32 s65, s39, 0
	s_add_i32 s53, s60, s57
	global_load_lds_dwordx4 v[218:219], off
	v_lshl_add_u64 v[252:253], s[64:65], 0, v[148:149]
	s_mov_b32 m0, s53
	v_lshl_add_u64 v[232:233], s[40:41], 0, v[150:151]
	global_load_lds_dwordx4 v[252:253], off
	v_lshl_add_u64 v[252:253], s[64:65], 0, v[152:153]
	s_add_i32 m0, s53, 0x2000
	s_nop 0
	global_load_lds_dwordx4 v[252:253], off
	v_lshl_add_u64 v[252:253], s[40:41], 0, v[146:147]
	s_mov_b32 m0, s37
	s_nop 0
	global_load_lds_dwordx4 v[252:253], off
	s_mov_b32 m0, s58
	s_nop 0
	global_load_lds_dwordx4 v[232:233], off
	s_waitcnt vmcnt(8)
	s_waitcnt lgkmcnt(0)
	s_barrier
	s_setprio 1
	v_mfma_f32_16x16x32_bf16 v[30:33], v[106:109], v[202:205], v[30:33]
	v_mfma_f32_16x16x32_bf16 v[26:29], v[114:117], v[202:205], v[26:29]
	v_mfma_f32_16x16x32_bf16 v[22:25], v[106:109], v[210:213], v[22:25]
	v_mfma_f32_16x16x32_bf16 v[18:21], v[114:117], v[210:213], v[18:21]
	v_mfma_f32_16x16x32_bf16 v[14:17], v[106:109], v[236:239], v[14:17]
	v_mfma_f32_16x16x32_bf16 v[10:13], v[114:117], v[236:239], v[10:13]
	v_mfma_f32_16x16x32_bf16 v[6:9], v[106:109], v[244:247], v[6:9]
	v_mfma_f32_16x16x32_bf16 v[2:5], v[114:117], v[244:247], v[2:5]
	v_mfma_f32_16x16x32_bf16 v[30:33], v[110:113], v[206:209], v[30:33]
	v_mfma_f32_16x16x32_bf16 v[26:29], v[118:121], v[206:209], v[26:29]
	v_mfma_f32_16x16x32_bf16 v[22:25], v[110:113], v[214:217], v[22:25]
	v_mfma_f32_16x16x32_bf16 v[18:21], v[118:121], v[214:217], v[18:21]
	v_mfma_f32_16x16x32_bf16 v[14:17], v[110:113], v[240:243], v[14:17]
	v_mfma_f32_16x16x32_bf16 v[10:13], v[118:121], v[240:243], v[10:13]
	v_mfma_f32_16x16x32_bf16 v[6:9], v[110:113], v[248:251], v[6:9]
	v_mfma_f32_16x16x32_bf16 v[2:5], v[118:121], v[248:251], v[2:5]
	s_setprio 0
	s_setprio 1
	v_mfma_f32_16x16x32_bf16 v[94:97], v[160:163], v[202:205], v[94:97]
	v_mfma_f32_16x16x32_bf16 v[90:93], v[194:197], v[202:205], v[90:93]
	v_mfma_f32_16x16x32_bf16 v[86:89], v[160:163], v[210:213], v[86:89]
	v_mfma_f32_16x16x32_bf16 v[82:85], v[194:197], v[210:213], v[82:85]
	v_mfma_f32_16x16x32_bf16 v[78:81], v[160:163], v[236:239], v[78:81]
	v_mfma_f32_16x16x32_bf16 v[74:77], v[194:197], v[236:239], v[74:77]
	v_mfma_f32_16x16x32_bf16 v[62:65], v[160:163], v[244:247], v[62:65]
	v_mfma_f32_16x16x32_bf16 v[58:61], v[194:197], v[244:247], v[58:61]
	v_mfma_f32_16x16x32_bf16 v[94:97], v[164:167], v[206:209], v[94:97]
	v_mfma_f32_16x16x32_bf16 v[90:93], v[198:201], v[206:209], v[90:93]
	v_mfma_f32_16x16x32_bf16 v[86:89], v[164:167], v[214:217], v[86:89]
	v_mfma_f32_16x16x32_bf16 v[82:85], v[198:201], v[214:217], v[82:85]
	v_mfma_f32_16x16x32_bf16 v[78:81], v[164:167], v[240:243], v[78:81]
	v_mfma_f32_16x16x32_bf16 v[74:77], v[198:201], v[240:243], v[74:77]
	v_mfma_f32_16x16x32_bf16 v[62:65], v[164:167], v[248:251], v[62:65]
	v_mfma_f32_16x16x32_bf16 v[58:61], v[198:201], v[248:251], v[58:61]
	s_setprio 0
	s_barrier
	s_add_i32 s53, 0, 0x18000
	v_add_u32_e32 v0, s53, v182
	s_add_i32 s60, 0, 0x1c000
	ds_read_b128 v[106:109], v0
	ds_read_b128 v[110:113], v0 offset:1024
	ds_read_b128 v[114:117], v0 offset:2048
	ds_read_b128 v[118:121], v0 offset:3072
	v_add_u32_e32 v0, s60, v182
	ds_read_b128 v[160:163], v0
	ds_read_b128 v[164:167], v0 offset:1024
	ds_read_b128 v[194:197], v0 offset:2048
	ds_read_b128 v[198:201], v0 offset:3072
	s_add_u32 s40, s40, 0x40000
	s_addc_u32 s41, s41, 0
	s_mov_b32 m0, s59
	v_lshl_add_u64 v[222:223], s[40:41], 0, v[146:147]
	ds_read_b128 v[202:205], v192 offset:32768
	ds_read_b128 v[206:209], v192 offset:33792
	ds_read_b128 v[210:213], v192 offset:34816
	ds_read_b128 v[214:217], v192 offset:35840
	ds_read_b128 v[236:239], v192 offset:36864
	ds_read_b128 v[240:243], v192 offset:37888
	ds_read_b128 v[244:247], v192 offset:38912
	ds_read_b128 v[248:251], v192 offset:39936
	global_load_lds_dwordx4 v[222:223], off
	v_lshl_add_u64 v[222:223], s[40:41], 0, v[150:151]
	s_mov_b32 m0, s74
	s_nop 0
	global_load_lds_dwordx4 v[222:223], off
	s_waitcnt vmcnt(8)
	s_waitcnt lgkmcnt(0)
	s_barrier
	s_setprio 1
	v_mfma_f32_16x16x32_bf16 v[70:73], v[106:109], v[202:205], v[70:73]
	v_mfma_f32_16x16x32_bf16 v[66:69], v[114:117], v[202:205], v[66:69]
	v_mfma_f32_16x16x32_bf16 v[54:57], v[106:109], v[210:213], v[54:57]
	v_mfma_f32_16x16x32_bf16 v[50:53], v[114:117], v[210:213], v[50:53]
	v_mfma_f32_16x16x32_bf16 v[46:49], v[106:109], v[236:239], v[46:49]
	v_mfma_f32_16x16x32_bf16 v[42:45], v[114:117], v[236:239], v[42:45]
	v_mfma_f32_16x16x32_bf16 v[38:41], v[106:109], v[244:247], v[38:41]
	v_mfma_f32_16x16x32_bf16 v[34:37], v[114:117], v[244:247], v[34:37]
	v_mfma_f32_16x16x32_bf16 v[70:73], v[110:113], v[206:209], v[70:73]
	v_mfma_f32_16x16x32_bf16 v[66:69], v[118:121], v[206:209], v[66:69]
	v_mfma_f32_16x16x32_bf16 v[54:57], v[110:113], v[214:217], v[54:57]
	v_mfma_f32_16x16x32_bf16 v[50:53], v[118:121], v[214:217], v[50:53]
	v_mfma_f32_16x16x32_bf16 v[46:49], v[110:113], v[240:243], v[46:49]
	v_mfma_f32_16x16x32_bf16 v[42:45], v[118:121], v[240:243], v[42:45]
	v_mfma_f32_16x16x32_bf16 v[38:41], v[110:113], v[248:251], v[38:41]
	v_mfma_f32_16x16x32_bf16 v[34:37], v[118:121], v[248:251], v[34:37]
	s_setprio 0
	s_setprio 1
	v_mfma_f32_16x16x32_bf16 v[142:145], v[160:163], v[202:205], v[142:145]
	v_mfma_f32_16x16x32_bf16 v[138:141], v[194:197], v[202:205], v[138:141]
	v_mfma_f32_16x16x32_bf16 v[134:137], v[160:163], v[210:213], v[134:137]
	v_mfma_f32_16x16x32_bf16 v[130:133], v[194:197], v[210:213], v[130:133]
	v_mfma_f32_16x16x32_bf16 v[126:129], v[160:163], v[236:239], v[126:129]
	v_mfma_f32_16x16x32_bf16 v[122:125], v[194:197], v[236:239], v[122:125]
	v_mfma_f32_16x16x32_bf16 v[102:105], v[160:163], v[244:247], v[102:105]
	v_mfma_f32_16x16x32_bf16 v[98:101], v[194:197], v[244:247], v[98:101]
	v_mfma_f32_16x16x32_bf16 v[142:145], v[164:167], v[206:209], v[142:145]
	v_mfma_f32_16x16x32_bf16 v[138:141], v[198:201], v[206:209], v[138:141]
	v_mfma_f32_16x16x32_bf16 v[134:137], v[164:167], v[214:217], v[134:137]
	v_mfma_f32_16x16x32_bf16 v[130:133], v[198:201], v[214:217], v[130:133]
	v_mfma_f32_16x16x32_bf16 v[126:129], v[164:167], v[240:243], v[126:129]
	v_mfma_f32_16x16x32_bf16 v[122:125], v[198:201], v[240:243], v[122:125]
	v_mfma_f32_16x16x32_bf16 v[102:105], v[164:167], v[248:251], v[102:105]
	v_mfma_f32_16x16x32_bf16 v[98:101], v[198:201], v[248:251], v[98:101]
	s_setprio 0
	s_barrier
	s_add_i32 s40, s53, s57
	v_lshl_add_u64 v[168:169], v[168:169], 0, s[54:55]
	s_mov_b32 m0, s40
	ds_read_b128 v[202:205], v192 offset:49152
	ds_read_b128 v[206:209], v192 offset:50176
	ds_read_b128 v[210:213], v192 offset:51200
	ds_read_b128 v[214:217], v192 offset:52224
	ds_read_b128 v[236:239], v192 offset:53248
	ds_read_b128 v[240:243], v192 offset:54272
	ds_read_b128 v[244:247], v192 offset:55296
	ds_read_b128 v[248:251], v192 offset:56320
	global_load_lds_dwordx4 v[168:169], off
	s_add_i32 m0, s40, 0x2000
	s_add_u32 s38, s38, 0x40080
	v_lshl_add_u64 v[168:169], v[218:219], 0, s[54:55]
	s_addc_u32 s39, s39, 0
	s_add_i32 s40, s60, s57
	global_load_lds_dwordx4 v[168:169], off
	v_lshl_add_u64 v[168:169], s[38:39], 0, v[148:149]
	s_mov_b32 m0, s40
	s_nop 0
	global_load_lds_dwordx4 v[168:169], off
	v_lshl_add_u64 v[168:169], s[38:39], 0, v[152:153]
	s_add_i32 m0, s40, 0x2000
	s_nop 0
	global_load_lds_dwordx4 v[168:169], off
	v_lshl_add_u64 v[168:169], v[252:253], 0, s[54:55]
	s_mov_b32 m0, s79
	s_nop 0
	global_load_lds_dwordx4 v[168:169], off
	v_lshl_add_u64 v[168:169], v[232:233], 0, s[54:55]
	s_mov_b32 m0, s80
	s_nop 0
	global_load_lds_dwordx4 v[168:169], off
	s_waitcnt vmcnt(8)
	s_waitcnt lgkmcnt(0)
	s_barrier
	s_setprio 1
	v_mfma_f32_16x16x32_bf16 v[30:33], v[106:109], v[202:205], v[30:33]
	v_mfma_f32_16x16x32_bf16 v[26:29], v[114:117], v[202:205], v[26:29]
	v_mfma_f32_16x16x32_bf16 v[22:25], v[106:109], v[210:213], v[22:25]
	v_mfma_f32_16x16x32_bf16 v[18:21], v[114:117], v[210:213], v[18:21]
	v_mfma_f32_16x16x32_bf16 v[14:17], v[106:109], v[236:239], v[14:17]
	v_mfma_f32_16x16x32_bf16 v[10:13], v[114:117], v[236:239], v[10:13]
	v_mfma_f32_16x16x32_bf16 v[6:9], v[106:109], v[244:247], v[6:9]
	v_mfma_f32_16x16x32_bf16 v[2:5], v[114:117], v[244:247], v[2:5]
	v_mfma_f32_16x16x32_bf16 v[30:33], v[110:113], v[206:209], v[30:33]
	v_mfma_f32_16x16x32_bf16 v[26:29], v[118:121], v[206:209], v[26:29]
	v_mfma_f32_16x16x32_bf16 v[22:25], v[110:113], v[214:217], v[22:25]
	v_mfma_f32_16x16x32_bf16 v[18:21], v[118:121], v[214:217], v[18:21]
	v_mfma_f32_16x16x32_bf16 v[14:17], v[110:113], v[240:243], v[14:17]
	v_mfma_f32_16x16x32_bf16 v[10:13], v[118:121], v[240:243], v[10:13]
	v_mfma_f32_16x16x32_bf16 v[6:9], v[110:113], v[248:251], v[6:9]
	v_mfma_f32_16x16x32_bf16 v[2:5], v[118:121], v[248:251], v[2:5]
	s_setprio 0
	s_setprio 1
	v_mfma_f32_16x16x32_bf16 v[94:97], v[160:163], v[202:205], v[94:97]
	v_mfma_f32_16x16x32_bf16 v[90:93], v[194:197], v[202:205], v[90:93]
	v_mfma_f32_16x16x32_bf16 v[86:89], v[160:163], v[210:213], v[86:89]
	v_mfma_f32_16x16x32_bf16 v[82:85], v[194:197], v[210:213], v[82:85]
	v_mfma_f32_16x16x32_bf16 v[78:81], v[160:163], v[236:239], v[78:81]
	v_mfma_f32_16x16x32_bf16 v[74:77], v[194:197], v[236:239], v[74:77]
	v_mfma_f32_16x16x32_bf16 v[62:65], v[160:163], v[244:247], v[62:65]
	v_mfma_f32_16x16x32_bf16 v[58:61], v[194:197], v[244:247], v[58:61]
	v_mfma_f32_16x16x32_bf16 v[94:97], v[164:167], v[206:209], v[94:97]
	v_mfma_f32_16x16x32_bf16 v[90:93], v[198:201], v[206:209], v[90:93]
	v_mfma_f32_16x16x32_bf16 v[86:89], v[164:167], v[214:217], v[86:89]
	v_mfma_f32_16x16x32_bf16 v[82:85], v[198:201], v[214:217], v[82:85]
	v_mfma_f32_16x16x32_bf16 v[78:81], v[164:167], v[240:243], v[78:81]
	v_mfma_f32_16x16x32_bf16 v[74:77], v[198:201], v[240:243], v[74:77]
	v_mfma_f32_16x16x32_bf16 v[62:65], v[164:167], v[248:251], v[62:65]
	v_mfma_f32_16x16x32_bf16 v[58:61], v[198:201], v[248:251], v[58:61]
	s_setprio 0
	s_barrier
	s_add_i32 s43, s43, 2
	s_add_u32 s8, s8, 0x100
	s_addc_u32 s9, s9, 0
	s_add_u32 s29, s29, 0x100
	s_addc_u32 s42, s42, 0
	s_cmp_gt_u32 s43, 13
	s_cbranch_scc0 .LBB0_613
	s_and_b64 vcc, exec, s[24:25]
	s_cbranch_vccz .LBB0_620
	s_barrier
	s_cmp_lg_u32 s10, 12
	s_mov_b64 s[8:9], -1
	s_cbranch_scc1 .LBB0_621

.LBB0_973:
	s_add_u32 s30, s28, 0xfffc0080
	s_addc_u32 s31, s29, -1
	s_add_i32 s53, 0, 0x10000
	s_cmp_eq_u32 s50, 12
	s_cselect_b32 s35, s2, s31
	s_cselect_b32 s34, s3, s30
	s_cselect_b32 s31, s17, s27
	s_cselect_b32 s30, s19, s25
	s_add_i32 s60, 0, 0x14000
	v_add_u32_e32 v142, s53, v200
	v_add_u32_e32 v180, s60, v200
	ds_read_b128 v[130:133], v142
	ds_read_b128 v[134:137], v142 offset:1024
	ds_read_b128 v[138:141], v142 offset:2048
	ds_read_b128 v[142:145], v142 offset:3072
	ds_read_b128 v[146:149], v180
	ds_read_b128 v[150:153], v180 offset:1024
	ds_read_b128 v[154:157], v180 offset:2048
	ds_read_b128 v[180:183], v180 offset:3072
	v_lshl_add_u64 v[222:223], s[28:29], 0, v[166:167]
	s_add_i32 m0, s43, 0xc000
	ds_read_b128 v[184:187], v202
	ds_read_b128 v[188:191], v202 offset:1024
	ds_read_b128 v[192:195], v202 offset:2048
	ds_read_b128 v[196:199], v202 offset:3072
	ds_read_b128 v[204:207], v202 offset:4096
	ds_read_b128 v[208:211], v202 offset:5120
	ds_read_b128 v[212:215], v202 offset:6144
	ds_read_b128 v[216:219], v202 offset:7168
	global_load_lds_dwordx4 v[222:223], off
	v_lshl_add_u64 v[222:223], s[28:29], 0, v[168:169]
	s_add_i32 m0, s43, 0xe000
	s_nop 0
	global_load_lds_dwordx4 v[222:223], off
	s_waitcnt vmcnt(8)
	s_waitcnt lgkmcnt(0)
	s_barrier
	s_setprio 1
	v_mfma_f32_16x16x32_bf16 v[126:129], v[130:133], v[184:187], v[126:129]
	v_mfma_f32_16x16x32_bf16 v[122:125], v[138:141], v[184:187], v[122:125]
	v_mfma_f32_16x16x32_bf16 v[110:113], v[130:133], v[192:195], v[110:113]
	v_mfma_f32_16x16x32_bf16 v[106:109], v[138:141], v[192:195], v[106:109]
	v_mfma_f32_16x16x32_bf16 v[94:97], v[130:133], v[204:207], v[94:97]
	v_mfma_f32_16x16x32_bf16 v[90:93], v[138:141], v[204:207], v[90:93]
	v_mfma_f32_16x16x32_bf16 v[78:81], v[130:133], v[212:215], v[78:81]
	v_mfma_f32_16x16x32_bf16 v[74:77], v[138:141], v[212:215], v[74:77]
	v_mfma_f32_16x16x32_bf16 v[126:129], v[134:137], v[188:191], v[126:129]
	v_mfma_f32_16x16x32_bf16 v[122:125], v[142:145], v[188:191], v[122:125]
	v_mfma_f32_16x16x32_bf16 v[110:113], v[134:137], v[196:199], v[110:113]
	v_mfma_f32_16x16x32_bf16 v[106:109], v[142:145], v[196:199], v[106:109]
	v_mfma_f32_16x16x32_bf16 v[94:97], v[134:137], v[208:211], v[94:97]
	v_mfma_f32_16x16x32_bf16 v[90:93], v[142:145], v[208:211], v[90:93]
	v_mfma_f32_16x16x32_bf16 v[78:81], v[134:137], v[216:219], v[78:81]
	v_mfma_f32_16x16x32_bf16 v[74:77], v[142:145], v[216:219], v[74:77]
	s_setprio 0
	s_setprio 1
	v_mfma_f32_16x16x32_bf16 v[118:121], v[146:149], v[184:187], v[118:121]
	v_mfma_f32_16x16x32_bf16 v[114:117], v[154:157], v[184:187], v[114:117]
	v_mfma_f32_16x16x32_bf16 v[102:105], v[146:149], v[192:195], v[102:105]
	v_mfma_f32_16x16x32_bf16 v[98:101], v[154:157], v[192:195], v[98:101]
	v_mfma_f32_16x16x32_bf16 v[86:89], v[146:149], v[204:207], v[86:89]
	v_mfma_f32_16x16x32_bf16 v[82:85], v[154:157], v[204:207], v[82:85]
	v_mfma_f32_16x16x32_bf16 v[70:73], v[146:149], v[212:215], v[70:73]
	v_mfma_f32_16x16x32_bf16 v[66:69], v[154:157], v[212:215], v[66:69]
	v_mfma_f32_16x16x32_bf16 v[118:121], v[150:153], v[188:191], v[118:121]
	v_mfma_f32_16x16x32_bf16 v[114:117], v[180:183], v[188:191], v[114:117]
	v_mfma_f32_16x16x32_bf16 v[102:105], v[150:153], v[196:199], v[102:105]
	v_mfma_f32_16x16x32_bf16 v[98:101], v[180:183], v[196:199], v[98:101]
	v_mfma_f32_16x16x32_bf16 v[86:89], v[150:153], v[208:211], v[86:89]
	v_mfma_f32_16x16x32_bf16 v[82:85], v[180:183], v[208:211], v[82:85]
	v_mfma_f32_16x16x32_bf16 v[70:73], v[150:153], v[216:219], v[70:73]
	v_mfma_f32_16x16x32_bf16 v[66:69], v[180:183], v[216:219], v[66:69]
	s_setprio 0
	s_barrier
	s_add_i32 s53, s53, s42
	v_lshl_add_u64 v[222:223], s[30:31], 0, v[0:1]
	s_mov_b32 m0, s53
	ds_read_b128 v[184:187], v202 offset:16384
	ds_read_b128 v[188:191], v202 offset:17408
	ds_read_b128 v[192:195], v202 offset:18432
	ds_read_b128 v[196:199], v202 offset:19456
	ds_read_b128 v[204:207], v202 offset:20480
	ds_read_b128 v[208:211], v202 offset:21504
	ds_read_b128 v[212:215], v202 offset:22528
	ds_read_b128 v[216:219], v202 offset:23552
	global_load_lds_dwordx4 v[222:223], off
	s_add_i32 m0, s53, 0x2000
	s_add_u32 s64, s30, 0x40000
	v_lshl_add_u64 v[232:233], s[30:31], 0, v[162:163]
	s_addc_u32 s65, s31, 0
	s_add_i32 s53, s60, s42
	global_load_lds_dwordx4 v[232:233], off
	v_lshl_add_u64 v[236:237], s[64:65], 0, v[0:1]
	s_mov_b32 m0, s53
	v_lshl_add_u64 v[238:239], s[34:35], 0, v[160:161]
	global_load_lds_dwordx4 v[236:237], off
	v_lshl_add_u64 v[236:237], s[64:65], 0, v[162:163]
	s_add_i32 m0, s53, 0x2000
	s_nop 0
	global_load_lds_dwordx4 v[236:237], off
	v_lshl_add_u64 v[236:237], s[34:35], 0, v[158:159]
	s_mov_b32 m0, s43
	s_nop 0
	global_load_lds_dwordx4 v[236:237], off
	s_mov_b32 m0, s45
	s_nop 0
	global_load_lds_dwordx4 v[238:239], off
	s_waitcnt vmcnt(8)
	s_waitcnt lgkmcnt(0)
	s_barrier
	s_setprio 1
	v_mfma_f32_16x16x32_bf16 v[62:65], v[130:133], v[184:187], v[62:65]
	v_mfma_f32_16x16x32_bf16 v[58:61], v[138:141], v[184:187], v[58:61]
	v_mfma_f32_16x16x32_bf16 v[46:49], v[130:133], v[192:195], v[46:49]
	v_mfma_f32_16x16x32_bf16 v[42:45], v[138:141], v[192:195], v[42:45]
	v_mfma_f32_16x16x32_bf16 v[30:33], v[130:133], v[204:207], v[30:33]
	v_mfma_f32_16x16x32_bf16 v[26:29], v[138:141], v[204:207], v[26:29]
	v_mfma_f32_16x16x32_bf16 v[14:17], v[130:133], v[212:215], v[14:17]
	v_mfma_f32_16x16x32_bf16 v[10:13], v[138:141], v[212:215], v[10:13]
	v_mfma_f32_16x16x32_bf16 v[62:65], v[134:137], v[188:191], v[62:65]
	v_mfma_f32_16x16x32_bf16 v[58:61], v[142:145], v[188:191], v[58:61]
	v_mfma_f32_16x16x32_bf16 v[46:49], v[134:137], v[196:199], v[46:49]
	v_mfma_f32_16x16x32_bf16 v[42:45], v[142:145], v[196:199], v[42:45]
	v_mfma_f32_16x16x32_bf16 v[30:33], v[134:137], v[208:211], v[30:33]
	v_mfma_f32_16x16x32_bf16 v[26:29], v[142:145], v[208:211], v[26:29]
	v_mfma_f32_16x16x32_bf16 v[14:17], v[134:137], v[216:219], v[14:17]
	v_mfma_f32_16x16x32_bf16 v[10:13], v[142:145], v[216:219], v[10:13]
	s_setprio 0
	s_setprio 1
	v_mfma_f32_16x16x32_bf16 v[54:57], v[146:149], v[184:187], v[54:57]
	v_mfma_f32_16x16x32_bf16 v[50:53], v[154:157], v[184:187], v[50:53]
	v_mfma_f32_16x16x32_bf16 v[38:41], v[146:149], v[192:195], v[38:41]
	v_mfma_f32_16x16x32_bf16 v[34:37], v[154:157], v[192:195], v[34:37]
	v_mfma_f32_16x16x32_bf16 v[22:25], v[146:149], v[204:207], v[22:25]
	v_mfma_f32_16x16x32_bf16 v[18:21], v[154:157], v[204:207], v[18:21]
	v_mfma_f32_16x16x32_bf16 v[6:9], v[146:149], v[212:215], v[6:9]
	v_mfma_f32_16x16x32_bf16 v[2:5], v[154:157], v[212:215], v[2:5]
	v_mfma_f32_16x16x32_bf16 v[54:57], v[150:153], v[188:191], v[54:57]
	v_mfma_f32_16x16x32_bf16 v[50:53], v[180:183], v[188:191], v[50:53]
	v_mfma_f32_16x16x32_bf16 v[38:41], v[150:153], v[196:199], v[38:41]
	v_mfma_f32_16x16x32_bf16 v[34:37], v[180:183], v[196:199], v[34:37]
	v_mfma_f32_16x16x32_bf16 v[22:25], v[150:153], v[208:211], v[22:25]
	v_mfma_f32_16x16x32_bf16 v[18:21], v[180:183], v[208:211], v[18:21]
	v_mfma_f32_16x16x32_bf16 v[6:9], v[150:153], v[216:219], v[6:9]
	v_mfma_f32_16x16x32_bf16 v[2:5], v[180:183], v[216:219], v[2:5]
	s_setprio 0
	s_barrier
	s_add_i32 s53, 0, 0x18000
	s_add_i32 s60, 0, 0x1c000
	v_add_u32_e32 v142, s53, v200
	v_add_u32_e32 v180, s60, v200
	ds_read_b128 v[130:133], v142
	ds_read_b128 v[134:137], v142 offset:1024
	ds_read_b128 v[138:141], v142 offset:2048
	ds_read_b128 v[142:145], v142 offset:3072
	ds_read_b128 v[146:149], v180
	ds_read_b128 v[150:153], v180 offset:1024
	ds_read_b128 v[154:157], v180 offset:2048
	ds_read_b128 v[180:183], v180 offset:3072
	s_add_u32 s34, s34, 0x40000
	s_addc_u32 s35, s35, 0
	s_mov_b32 m0, s46
	v_lshl_add_u64 v[240:241], s[34:35], 0, v[158:159]
	ds_read_b128 v[184:187], v202 offset:32768
	ds_read_b128 v[188:191], v202 offset:33792
	ds_read_b128 v[192:195], v202 offset:34816
	ds_read_b128 v[196:199], v202 offset:35840
	ds_read_b128 v[204:207], v202 offset:36864
	ds_read_b128 v[208:211], v202 offset:37888
	ds_read_b128 v[212:215], v202 offset:38912
	ds_read_b128 v[216:219], v202 offset:39936
	global_load_lds_dwordx4 v[240:241], off
	v_lshl_add_u64 v[240:241], s[34:35], 0, v[160:161]
	s_mov_b32 m0, s47
	s_nop 0
	global_load_lds_dwordx4 v[240:241], off
	s_waitcnt vmcnt(8)
	s_waitcnt lgkmcnt(0)
	s_barrier
	s_setprio 1
	v_mfma_f32_16x16x32_bf16 v[126:129], v[130:133], v[184:187], v[126:129]
	v_mfma_f32_16x16x32_bf16 v[122:125], v[138:141], v[184:187], v[122:125]
	v_mfma_f32_16x16x32_bf16 v[110:113], v[130:133], v[192:195], v[110:113]
	v_mfma_f32_16x16x32_bf16 v[106:109], v[138:141], v[192:195], v[106:109]
	v_mfma_f32_16x16x32_bf16 v[94:97], v[130:133], v[204:207], v[94:97]
	v_mfma_f32_16x16x32_bf16 v[90:93], v[138:141], v[204:207], v[90:93]
	v_mfma_f32_16x16x32_bf16 v[78:81], v[130:133], v[212:215], v[78:81]
	v_mfma_f32_16x16x32_bf16 v[74:77], v[138:141], v[212:215], v[74:77]
	v_mfma_f32_16x16x32_bf16 v[126:129], v[134:137], v[188:191], v[126:129]
	v_mfma_f32_16x16x32_bf16 v[122:125], v[142:145], v[188:191], v[122:125]
	v_mfma_f32_16x16x32_bf16 v[110:113], v[134:137], v[196:199], v[110:113]
	v_mfma_f32_16x16x32_bf16 v[106:109], v[142:145], v[196:199], v[106:109]
	v_mfma_f32_16x16x32_bf16 v[94:97], v[134:137], v[208:211], v[94:97]
	v_mfma_f32_16x16x32_bf16 v[90:93], v[142:145], v[208:211], v[90:93]
	v_mfma_f32_16x16x32_bf16 v[78:81], v[134:137], v[216:219], v[78:81]
	v_mfma_f32_16x16x32_bf16 v[74:77], v[142:145], v[216:219], v[74:77]
	s_setprio 0
	s_setprio 1
	v_mfma_f32_16x16x32_bf16 v[118:121], v[146:149], v[184:187], v[118:121]
	v_mfma_f32_16x16x32_bf16 v[114:117], v[154:157], v[184:187], v[114:117]
	v_mfma_f32_16x16x32_bf16 v[102:105], v[146:149], v[192:195], v[102:105]
	v_mfma_f32_16x16x32_bf16 v[98:101], v[154:157], v[192:195], v[98:101]
	v_mfma_f32_16x16x32_bf16 v[86:89], v[146:149], v[204:207], v[86:89]
	v_mfma_f32_16x16x32_bf16 v[82:85], v[154:157], v[204:207], v[82:85]
	v_mfma_f32_16x16x32_bf16 v[70:73], v[146:149], v[212:215], v[70:73]
	v_mfma_f32_16x16x32_bf16 v[66:69], v[154:157], v[212:215], v[66:69]
	v_mfma_f32_16x16x32_bf16 v[118:121], v[150:153], v[188:191], v[118:121]
	v_mfma_f32_16x16x32_bf16 v[114:117], v[180:183], v[188:191], v[114:117]
	v_mfma_f32_16x16x32_bf16 v[102:105], v[150:153], v[196:199], v[102:105]
	v_mfma_f32_16x16x32_bf16 v[98:101], v[180:183], v[196:199], v[98:101]
	v_mfma_f32_16x16x32_bf16 v[86:89], v[150:153], v[208:211], v[86:89]
	v_mfma_f32_16x16x32_bf16 v[82:85], v[180:183], v[208:211], v[82:85]
	v_mfma_f32_16x16x32_bf16 v[70:73], v[150:153], v[216:219], v[70:73]
	v_mfma_f32_16x16x32_bf16 v[66:69], v[180:183], v[216:219], v[66:69]
	s_setprio 0
	s_barrier
	s_add_i32 s34, s53, s42
	v_lshl_add_u64 v[222:223], v[222:223], 0, s[54:55]
	s_mov_b32 m0, s34
	ds_read_b128 v[184:187], v202 offset:49152
	ds_read_b128 v[188:191], v202 offset:50176
	ds_read_b128 v[192:195], v202 offset:51200
	ds_read_b128 v[196:199], v202 offset:52224
	ds_read_b128 v[204:207], v202 offset:53248
	ds_read_b128 v[208:211], v202 offset:54272
	ds_read_b128 v[212:215], v202 offset:55296
	ds_read_b128 v[216:219], v202 offset:56320
	global_load_lds_dwordx4 v[222:223], off
	s_add_i32 m0, s34, 0x2000
	s_add_u32 s30, s30, 0x40080
	v_lshl_add_u64 v[222:223], v[232:233], 0, s[54:55]
	s_addc_u32 s31, s31, 0
	s_add_i32 s34, s60, s42
	global_load_lds_dwordx4 v[222:223], off
	v_lshl_add_u64 v[222:223], s[30:31], 0, v[0:1]
	s_mov_b32 m0, s34
	s_nop 0
	global_load_lds_dwordx4 v[222:223], off
	v_lshl_add_u64 v[222:223], s[30:31], 0, v[162:163]
	s_add_i32 m0, s34, 0x2000
	s_nop 0
	global_load_lds_dwordx4 v[222:223], off
	v_lshl_add_u64 v[222:223], v[236:237], 0, s[54:55]
	s_mov_b32 m0, s56
	s_nop 0
	global_load_lds_dwordx4 v[222:223], off
	v_lshl_add_u64 v[222:223], v[238:239], 0, s[54:55]
	s_mov_b32 m0, s57
	s_nop 0
	global_load_lds_dwordx4 v[222:223], off
	s_waitcnt vmcnt(8)
	s_waitcnt lgkmcnt(0)
	s_barrier
	s_setprio 1
	v_mfma_f32_16x16x32_bf16 v[62:65], v[130:133], v[184:187], v[62:65]
	v_mfma_f32_16x16x32_bf16 v[58:61], v[138:141], v[184:187], v[58:61]
	v_mfma_f32_16x16x32_bf16 v[46:49], v[130:133], v[192:195], v[46:49]
	v_mfma_f32_16x16x32_bf16 v[42:45], v[138:141], v[192:195], v[42:45]
	v_mfma_f32_16x16x32_bf16 v[30:33], v[130:133], v[204:207], v[30:33]
	v_mfma_f32_16x16x32_bf16 v[26:29], v[138:141], v[204:207], v[26:29]
	v_mfma_f32_16x16x32_bf16 v[14:17], v[130:133], v[212:215], v[14:17]
	v_mfma_f32_16x16x32_bf16 v[10:13], v[138:141], v[212:215], v[10:13]
	v_mfma_f32_16x16x32_bf16 v[62:65], v[134:137], v[188:191], v[62:65]
	v_mfma_f32_16x16x32_bf16 v[58:61], v[142:145], v[188:191], v[58:61]
	v_mfma_f32_16x16x32_bf16 v[46:49], v[134:137], v[196:199], v[46:49]
	v_mfma_f32_16x16x32_bf16 v[42:45], v[142:145], v[196:199], v[42:45]
	v_mfma_f32_16x16x32_bf16 v[30:33], v[134:137], v[208:211], v[30:33]
	v_mfma_f32_16x16x32_bf16 v[26:29], v[142:145], v[208:211], v[26:29]
	v_mfma_f32_16x16x32_bf16 v[14:17], v[134:137], v[216:219], v[14:17]
	v_mfma_f32_16x16x32_bf16 v[10:13], v[142:145], v[216:219], v[10:13]
	s_setprio 0
	s_setprio 1
	v_mfma_f32_16x16x32_bf16 v[54:57], v[146:149], v[184:187], v[54:57]
	v_mfma_f32_16x16x32_bf16 v[50:53], v[154:157], v[184:187], v[50:53]
	v_mfma_f32_16x16x32_bf16 v[38:41], v[146:149], v[192:195], v[38:41]
	v_mfma_f32_16x16x32_bf16 v[34:37], v[154:157], v[192:195], v[34:37]
	v_mfma_f32_16x16x32_bf16 v[22:25], v[146:149], v[204:207], v[22:25]
	v_mfma_f32_16x16x32_bf16 v[18:21], v[154:157], v[204:207], v[18:21]
	v_mfma_f32_16x16x32_bf16 v[6:9], v[146:149], v[212:215], v[6:9]
	v_mfma_f32_16x16x32_bf16 v[2:5], v[154:157], v[212:215], v[2:5]
	v_mfma_f32_16x16x32_bf16 v[54:57], v[150:153], v[188:191], v[54:57]
	v_mfma_f32_16x16x32_bf16 v[50:53], v[180:183], v[188:191], v[50:53]
	v_mfma_f32_16x16x32_bf16 v[38:41], v[150:153], v[196:199], v[38:41]
	v_mfma_f32_16x16x32_bf16 v[34:37], v[180:183], v[196:199], v[34:37]
	v_mfma_f32_16x16x32_bf16 v[22:25], v[150:153], v[208:211], v[22:25]
	v_mfma_f32_16x16x32_bf16 v[18:21], v[180:183], v[208:211], v[18:21]
	v_mfma_f32_16x16x32_bf16 v[6:9], v[150:153], v[216:219], v[6:9]
	v_mfma_f32_16x16x32_bf16 v[2:5], v[180:183], v[216:219], v[2:5]
	s_setprio 0
	s_barrier
	s_add_i32 s50, s50, 2
	s_add_u32 s28, s28, 0x100
	s_addc_u32 s29, s29, 0
	s_add_u32 s25, s25, 0x100
	s_addc_u32 s27, s27, 0
	s_cmp_gt_u32 s50, 13
	s_cbranch_scc0 .LBB0_973
	s_and_b64 vcc, exec, s[14:15]
	s_cbranch_vccz .LBB0_976
	s_barrier

.LBB0_1097:
	s_add_u32 s28, s26, 0xfffc0080
	s_addc_u32 s29, s27, -1
	s_add_i32 s59, 0, 0x10000
	s_cmp_eq_u32 s58, 12
	s_cselect_b32 s31, s19, s29
	s_cselect_b32 s30, s25, s28
	v_add_u32_e32 v140, s59, v143
	s_cselect_b32 s29, s17, s57
	s_cselect_b32 s28, s53, s56
	s_add_i32 s60, 0, 0x14000
	ds_read_b128 v[150:153], v140
	ds_read_b128 v[154:157], v140 offset:1024
	ds_read_b128 v[158:161], v140 offset:2048
	ds_read_b128 v[162:165], v140 offset:3072
	v_add_u32_e32 v140, s60, v143
	ds_read_b128 v[166:169], v140
	ds_read_b128 v[180:183], v140 offset:1024
	ds_read_b128 v[184:187], v140 offset:2048
	ds_read_b128 v[188:191], v140 offset:3072
	v_lshl_add_u64 v[140:141], s[26:27], 0, v[136:137]
	s_add_i32 m0, s41, 0xc000
	ds_read_b128 v[192:195], v149
	ds_read_b128 v[196:199], v149 offset:1024
	ds_read_b128 v[200:203], v149 offset:2048
	ds_read_b128 v[204:207], v149 offset:3072
	ds_read_b128 v[208:211], v149 offset:4096
	ds_read_b128 v[212:215], v149 offset:5120
	ds_read_b128 v[216:219], v149 offset:6144
	ds_read_b128 v[236:239], v149 offset:7168
	global_load_lds_dwordx4 v[140:141], off
	v_lshl_add_u64 v[140:141], s[26:27], 0, v[138:139]
	s_add_i32 m0, s41, 0xe000
	s_nop 0
	global_load_lds_dwordx4 v[140:141], off
	s_waitcnt vmcnt(8)
	s_waitcnt lgkmcnt(0)
	s_barrier
	s_setprio 1
	v_mfma_f32_16x16x32_bf16 v[126:129], v[150:153], v[192:195], v[126:129]
	v_mfma_f32_16x16x32_bf16 v[118:121], v[158:161], v[192:195], v[118:121]
	v_mfma_f32_16x16x32_bf16 v[110:113], v[150:153], v[200:203], v[110:113]
	v_mfma_f32_16x16x32_bf16 v[102:105], v[158:161], v[200:203], v[102:105]
	v_mfma_f32_16x16x32_bf16 v[94:97], v[150:153], v[208:211], v[94:97]
	v_mfma_f32_16x16x32_bf16 v[86:89], v[158:161], v[208:211], v[86:89]
	v_mfma_f32_16x16x32_bf16 v[78:81], v[150:153], v[216:219], v[78:81]
	v_mfma_f32_16x16x32_bf16 v[70:73], v[158:161], v[216:219], v[70:73]
	v_mfma_f32_16x16x32_bf16 v[126:129], v[154:157], v[196:199], v[126:129]
	v_mfma_f32_16x16x32_bf16 v[118:121], v[162:165], v[196:199], v[118:121]
	v_mfma_f32_16x16x32_bf16 v[110:113], v[154:157], v[204:207], v[110:113]
	v_mfma_f32_16x16x32_bf16 v[102:105], v[162:165], v[204:207], v[102:105]
	v_mfma_f32_16x16x32_bf16 v[94:97], v[154:157], v[212:215], v[94:97]
	v_mfma_f32_16x16x32_bf16 v[86:89], v[162:165], v[212:215], v[86:89]
	v_mfma_f32_16x16x32_bf16 v[78:81], v[154:157], v[236:239], v[78:81]
	v_mfma_f32_16x16x32_bf16 v[70:73], v[162:165], v[236:239], v[70:73]
	s_setprio 0
	s_setprio 1
	v_mfma_f32_16x16x32_bf16 v[122:125], v[166:169], v[192:195], v[122:125]
	v_mfma_f32_16x16x32_bf16 v[114:117], v[184:187], v[192:195], v[114:117]
	v_mfma_f32_16x16x32_bf16 v[106:109], v[166:169], v[200:203], v[106:109]
	v_mfma_f32_16x16x32_bf16 v[98:101], v[184:187], v[200:203], v[98:101]
	v_mfma_f32_16x16x32_bf16 v[90:93], v[166:169], v[208:211], v[90:93]
	v_mfma_f32_16x16x32_bf16 v[82:85], v[184:187], v[208:211], v[82:85]
	v_mfma_f32_16x16x32_bf16 v[74:77], v[166:169], v[216:219], v[74:77]
	v_mfma_f32_16x16x32_bf16 v[66:69], v[184:187], v[216:219], v[66:69]
	v_mfma_f32_16x16x32_bf16 v[122:125], v[180:183], v[196:199], v[122:125]
	v_mfma_f32_16x16x32_bf16 v[114:117], v[188:191], v[196:199], v[114:117]
	v_mfma_f32_16x16x32_bf16 v[106:109], v[180:183], v[204:207], v[106:109]
	v_mfma_f32_16x16x32_bf16 v[98:101], v[188:191], v[204:207], v[98:101]
	v_mfma_f32_16x16x32_bf16 v[90:93], v[180:183], v[212:215], v[90:93]
	v_mfma_f32_16x16x32_bf16 v[82:85], v[188:191], v[212:215], v[82:85]
	v_mfma_f32_16x16x32_bf16 v[74:77], v[180:183], v[236:239], v[74:77]
	v_mfma_f32_16x16x32_bf16 v[66:69], v[188:191], v[236:239], v[66:69]
	s_setprio 0
	s_barrier
	s_add_i32 s59, s59, s38
	v_lshl_add_u64 v[140:141], s[28:29], 0, v[0:1]
	s_mov_b32 m0, s59
	ds_read_b128 v[192:195], v149 offset:16384
	ds_read_b128 v[196:199], v149 offset:17408
	ds_read_b128 v[200:203], v149 offset:18432
	ds_read_b128 v[204:207], v149 offset:19456
	ds_read_b128 v[208:211], v149 offset:20480
	ds_read_b128 v[212:215], v149 offset:21504
	ds_read_b128 v[216:219], v149 offset:22528
	ds_read_b128 v[236:239], v149 offset:23552
	global_load_lds_dwordx4 v[140:141], off
	s_add_i32 m0, s59, 0x2000
	s_add_u32 s64, s28, 0x40000
	v_lshl_add_u64 v[222:223], s[28:29], 0, v[130:131]
	s_addc_u32 s65, s29, 0
	s_add_i32 s59, s60, s38
	global_load_lds_dwordx4 v[222:223], off
	v_lshl_add_u64 v[232:233], s[64:65], 0, v[0:1]
	s_mov_b32 m0, s59
	v_lshl_add_u64 v[240:241], s[30:31], 0, v[132:133]
	global_load_lds_dwordx4 v[232:233], off
	v_lshl_add_u64 v[232:233], s[64:65], 0, v[130:131]
	s_add_i32 m0, s59, 0x2000
	s_nop 0
	global_load_lds_dwordx4 v[232:233], off
	v_lshl_add_u64 v[232:233], s[30:31], 0, v[134:135]
	s_mov_b32 m0, s41
	s_nop 0
	global_load_lds_dwordx4 v[232:233], off
	s_mov_b32 m0, s42
	s_nop 0
	global_load_lds_dwordx4 v[240:241], off
	s_waitcnt vmcnt(8)
	s_waitcnt lgkmcnt(0)
	s_barrier
	s_setprio 1
	v_mfma_f32_16x16x32_bf16 v[62:65], v[150:153], v[192:195], v[62:65]
	v_mfma_f32_16x16x32_bf16 v[54:57], v[158:161], v[192:195], v[54:57]
	v_mfma_f32_16x16x32_bf16 v[46:49], v[150:153], v[200:203], v[46:49]
	v_mfma_f32_16x16x32_bf16 v[38:41], v[158:161], v[200:203], v[38:41]
	v_mfma_f32_16x16x32_bf16 v[30:33], v[150:153], v[208:211], v[30:33]
	v_mfma_f32_16x16x32_bf16 v[22:25], v[158:161], v[208:211], v[22:25]
	v_mfma_f32_16x16x32_bf16 v[14:17], v[150:153], v[216:219], v[14:17]
	v_mfma_f32_16x16x32_bf16 v[6:9], v[158:161], v[216:219], v[6:9]
	v_mfma_f32_16x16x32_bf16 v[62:65], v[154:157], v[196:199], v[62:65]
	v_mfma_f32_16x16x32_bf16 v[54:57], v[162:165], v[196:199], v[54:57]
	v_mfma_f32_16x16x32_bf16 v[46:49], v[154:157], v[204:207], v[46:49]
	v_mfma_f32_16x16x32_bf16 v[38:41], v[162:165], v[204:207], v[38:41]
	v_mfma_f32_16x16x32_bf16 v[30:33], v[154:157], v[212:215], v[30:33]
	v_mfma_f32_16x16x32_bf16 v[22:25], v[162:165], v[212:215], v[22:25]
	v_mfma_f32_16x16x32_bf16 v[14:17], v[154:157], v[236:239], v[14:17]
	v_mfma_f32_16x16x32_bf16 v[6:9], v[162:165], v[236:239], v[6:9]
	s_setprio 0
	s_setprio 1
	v_mfma_f32_16x16x32_bf16 v[58:61], v[166:169], v[192:195], v[58:61]
	v_mfma_f32_16x16x32_bf16 v[50:53], v[184:187], v[192:195], v[50:53]
	v_mfma_f32_16x16x32_bf16 v[42:45], v[166:169], v[200:203], v[42:45]
	v_mfma_f32_16x16x32_bf16 v[34:37], v[184:187], v[200:203], v[34:37]
	v_mfma_f32_16x16x32_bf16 v[26:29], v[166:169], v[208:211], v[26:29]
	v_mfma_f32_16x16x32_bf16 v[18:21], v[184:187], v[208:211], v[18:21]
	v_mfma_f32_16x16x32_bf16 v[10:13], v[166:169], v[216:219], v[10:13]
	v_mfma_f32_16x16x32_bf16 v[2:5], v[184:187], v[216:219], v[2:5]
	v_mfma_f32_16x16x32_bf16 v[58:61], v[180:183], v[196:199], v[58:61]
	v_mfma_f32_16x16x32_bf16 v[50:53], v[188:191], v[196:199], v[50:53]
	v_mfma_f32_16x16x32_bf16 v[42:45], v[180:183], v[204:207], v[42:45]
	v_mfma_f32_16x16x32_bf16 v[34:37], v[188:191], v[204:207], v[34:37]
	v_mfma_f32_16x16x32_bf16 v[26:29], v[180:183], v[212:215], v[26:29]
	v_mfma_f32_16x16x32_bf16 v[18:21], v[188:191], v[212:215], v[18:21]
	v_mfma_f32_16x16x32_bf16 v[10:13], v[180:183], v[236:239], v[10:13]
	v_mfma_f32_16x16x32_bf16 v[2:5], v[188:191], v[236:239], v[2:5]
	s_setprio 0
	s_barrier
	s_add_i32 s59, 0, 0x18000
	s_add_i32 s60, 0, 0x1c000
	v_add_u32_e32 v162, s59, v143
	v_add_u32_e32 v188, s60, v143
	ds_read_b128 v[150:153], v162
	ds_read_b128 v[154:157], v162 offset:1024
	ds_read_b128 v[158:161], v162 offset:2048
	ds_read_b128 v[162:165], v162 offset:3072
	ds_read_b128 v[166:169], v188
	ds_read_b128 v[180:183], v188 offset:1024
	ds_read_b128 v[184:187], v188 offset:2048
	ds_read_b128 v[188:191], v188 offset:3072
	s_add_u32 s30, s30, 0x40000
	s_addc_u32 s31, s31, 0
	s_mov_b32 m0, s43
	v_lshl_add_u64 v[242:243], s[30:31], 0, v[134:135]
	ds_read_b128 v[192:195], v149 offset:32768
	ds_read_b128 v[196:199], v149 offset:33792
	ds_read_b128 v[200:203], v149 offset:34816
	ds_read_b128 v[204:207], v149 offset:35840
	ds_read_b128 v[208:211], v149 offset:36864
	ds_read_b128 v[212:215], v149 offset:37888
	ds_read_b128 v[216:219], v149 offset:38912
	ds_read_b128 v[236:239], v149 offset:39936
	global_load_lds_dwordx4 v[242:243], off
	v_lshl_add_u64 v[242:243], s[30:31], 0, v[132:133]
	s_mov_b32 m0, s46
	s_nop 0
	global_load_lds_dwordx4 v[242:243], off
	s_waitcnt vmcnt(8)
	s_waitcnt lgkmcnt(0)
	s_barrier
	s_setprio 1
	v_mfma_f32_16x16x32_bf16 v[126:129], v[150:153], v[192:195], v[126:129]
	v_mfma_f32_16x16x32_bf16 v[118:121], v[158:161], v[192:195], v[118:121]
	v_mfma_f32_16x16x32_bf16 v[110:113], v[150:153], v[200:203], v[110:113]
	v_mfma_f32_16x16x32_bf16 v[102:105], v[158:161], v[200:203], v[102:105]
	v_mfma_f32_16x16x32_bf16 v[94:97], v[150:153], v[208:211], v[94:97]
	v_mfma_f32_16x16x32_bf16 v[86:89], v[158:161], v[208:211], v[86:89]
	v_mfma_f32_16x16x32_bf16 v[78:81], v[150:153], v[216:219], v[78:81]
	v_mfma_f32_16x16x32_bf16 v[70:73], v[158:161], v[216:219], v[70:73]
	v_mfma_f32_16x16x32_bf16 v[126:129], v[154:157], v[196:199], v[126:129]
	v_mfma_f32_16x16x32_bf16 v[118:121], v[162:165], v[196:199], v[118:121]
	v_mfma_f32_16x16x32_bf16 v[110:113], v[154:157], v[204:207], v[110:113]
	v_mfma_f32_16x16x32_bf16 v[102:105], v[162:165], v[204:207], v[102:105]
	v_mfma_f32_16x16x32_bf16 v[94:97], v[154:157], v[212:215], v[94:97]
	v_mfma_f32_16x16x32_bf16 v[86:89], v[162:165], v[212:215], v[86:89]
	v_mfma_f32_16x16x32_bf16 v[78:81], v[154:157], v[236:239], v[78:81]
	v_mfma_f32_16x16x32_bf16 v[70:73], v[162:165], v[236:239], v[70:73]
	s_setprio 0
	s_setprio 1
	v_mfma_f32_16x16x32_bf16 v[122:125], v[166:169], v[192:195], v[122:125]
	v_mfma_f32_16x16x32_bf16 v[114:117], v[184:187], v[192:195], v[114:117]
	v_mfma_f32_16x16x32_bf16 v[106:109], v[166:169], v[200:203], v[106:109]
	v_mfma_f32_16x16x32_bf16 v[98:101], v[184:187], v[200:203], v[98:101]
	v_mfma_f32_16x16x32_bf16 v[90:93], v[166:169], v[208:211], v[90:93]
	v_mfma_f32_16x16x32_bf16 v[82:85], v[184:187], v[208:211], v[82:85]
	v_mfma_f32_16x16x32_bf16 v[74:77], v[166:169], v[216:219], v[74:77]
	v_mfma_f32_16x16x32_bf16 v[66:69], v[184:187], v[216:219], v[66:69]
	v_mfma_f32_16x16x32_bf16 v[122:125], v[180:183], v[196:199], v[122:125]
	v_mfma_f32_16x16x32_bf16 v[114:117], v[188:191], v[196:199], v[114:117]
	v_mfma_f32_16x16x32_bf16 v[106:109], v[180:183], v[204:207], v[106:109]
	v_mfma_f32_16x16x32_bf16 v[98:101], v[188:191], v[204:207], v[98:101]
	v_mfma_f32_16x16x32_bf16 v[90:93], v[180:183], v[212:215], v[90:93]
	v_mfma_f32_16x16x32_bf16 v[82:85], v[188:191], v[212:215], v[82:85]
	v_mfma_f32_16x16x32_bf16 v[74:77], v[180:183], v[236:239], v[74:77]
	v_mfma_f32_16x16x32_bf16 v[66:69], v[188:191], v[236:239], v[66:69]
	s_setprio 0
	s_barrier
	s_add_i32 s30, s59, s38
	v_lshl_add_u64 v[140:141], v[140:141], 0, s[54:55]
	s_mov_b32 m0, s30
	ds_read_b128 v[192:195], v149 offset:49152
	ds_read_b128 v[196:199], v149 offset:50176
	ds_read_b128 v[200:203], v149 offset:51200
	ds_read_b128 v[204:207], v149 offset:52224
	ds_read_b128 v[208:211], v149 offset:53248
	ds_read_b128 v[212:215], v149 offset:54272
	ds_read_b128 v[216:219], v149 offset:55296
	ds_read_b128 v[236:239], v149 offset:56320
	global_load_lds_dwordx4 v[140:141], off
	s_add_i32 m0, s30, 0x2000
	s_add_u32 s28, s28, 0x40080
	v_lshl_add_u64 v[140:141], v[222:223], 0, s[54:55]
	s_addc_u32 s29, s29, 0
	s_add_i32 s30, s60, s38
	global_load_lds_dwordx4 v[140:141], off
	v_lshl_add_u64 v[140:141], s[28:29], 0, v[0:1]
	s_mov_b32 m0, s30
	s_nop 0
	global_load_lds_dwordx4 v[140:141], off
	v_lshl_add_u64 v[140:141], s[28:29], 0, v[130:131]
	s_add_i32 m0, s30, 0x2000
	s_nop 0
	global_load_lds_dwordx4 v[140:141], off
	v_lshl_add_u64 v[140:141], v[232:233], 0, s[54:55]
	s_mov_b32 m0, s47
	s_nop 0
	global_load_lds_dwordx4 v[140:141], off
	v_lshl_add_u64 v[140:141], v[240:241], 0, s[54:55]
	s_mov_b32 m0, s50
	s_nop 0
	global_load_lds_dwordx4 v[140:141], off
	s_waitcnt vmcnt(8)
	s_waitcnt lgkmcnt(0)
	s_barrier
	s_setprio 1
	v_mfma_f32_16x16x32_bf16 v[62:65], v[150:153], v[192:195], v[62:65]
	v_mfma_f32_16x16x32_bf16 v[54:57], v[158:161], v[192:195], v[54:57]
	v_mfma_f32_16x16x32_bf16 v[46:49], v[150:153], v[200:203], v[46:49]
	v_mfma_f32_16x16x32_bf16 v[38:41], v[158:161], v[200:203], v[38:41]
	v_mfma_f32_16x16x32_bf16 v[30:33], v[150:153], v[208:211], v[30:33]
	v_mfma_f32_16x16x32_bf16 v[22:25], v[158:161], v[208:211], v[22:25]
	v_mfma_f32_16x16x32_bf16 v[14:17], v[150:153], v[216:219], v[14:17]
	v_mfma_f32_16x16x32_bf16 v[6:9], v[158:161], v[216:219], v[6:9]
	v_mfma_f32_16x16x32_bf16 v[62:65], v[154:157], v[196:199], v[62:65]
	v_mfma_f32_16x16x32_bf16 v[54:57], v[162:165], v[196:199], v[54:57]
	v_mfma_f32_16x16x32_bf16 v[46:49], v[154:157], v[204:207], v[46:49]
	v_mfma_f32_16x16x32_bf16 v[38:41], v[162:165], v[204:207], v[38:41]
	v_mfma_f32_16x16x32_bf16 v[30:33], v[154:157], v[212:215], v[30:33]
	v_mfma_f32_16x16x32_bf16 v[22:25], v[162:165], v[212:215], v[22:25]
	v_mfma_f32_16x16x32_bf16 v[14:17], v[154:157], v[236:239], v[14:17]
	v_mfma_f32_16x16x32_bf16 v[6:9], v[162:165], v[236:239], v[6:9]
	s_setprio 0
	s_setprio 1
	v_mfma_f32_16x16x32_bf16 v[58:61], v[166:169], v[192:195], v[58:61]
	v_mfma_f32_16x16x32_bf16 v[50:53], v[184:187], v[192:195], v[50:53]
	v_mfma_f32_16x16x32_bf16 v[42:45], v[166:169], v[200:203], v[42:45]
	v_mfma_f32_16x16x32_bf16 v[34:37], v[184:187], v[200:203], v[34:37]
	v_mfma_f32_16x16x32_bf16 v[26:29], v[166:169], v[208:211], v[26:29]
	v_mfma_f32_16x16x32_bf16 v[18:21], v[184:187], v[208:211], v[18:21]
	v_mfma_f32_16x16x32_bf16 v[10:13], v[166:169], v[216:219], v[10:13]
	v_mfma_f32_16x16x32_bf16 v[2:5], v[184:187], v[216:219], v[2:5]
	v_mfma_f32_16x16x32_bf16 v[58:61], v[180:183], v[196:199], v[58:61]
	v_mfma_f32_16x16x32_bf16 v[50:53], v[188:191], v[196:199], v[50:53]
	v_mfma_f32_16x16x32_bf16 v[42:45], v[180:183], v[204:207], v[42:45]
	v_mfma_f32_16x16x32_bf16 v[34:37], v[188:191], v[204:207], v[34:37]
	v_mfma_f32_16x16x32_bf16 v[26:29], v[180:183], v[212:215], v[26:29]
	v_mfma_f32_16x16x32_bf16 v[18:21], v[188:191], v[212:215], v[18:21]
	v_mfma_f32_16x16x32_bf16 v[10:13], v[180:183], v[236:239], v[10:13]
	v_mfma_f32_16x16x32_bf16 v[2:5], v[188:191], v[236:239], v[2:5]
	s_setprio 0
	s_barrier
	s_add_i32 s58, s58, 2
	s_add_u32 s26, s26, 0x100
	s_addc_u32 s27, s27, 0
	s_add_u32 s56, s56, 0x100
	s_addc_u32 s57, s57, 0
	s_cmp_gt_u32 s58, 13
	s_cbranch_scc0 .LBB0_1097
	s_and_b64 vcc, exec, s[14:15]
	s_cbranch_vccz .LBB0_1100
	s_barrier

.LBB0_1197:
	s_add_u32 s8, s30, 0x100
	s_addc_u32 s9, s31, 0
	s_add_i32 s53, 0, 0x10000
	s_cmp_eq_u32 s29, 40
	s_cselect_b32 s37, s25, s9
	s_cselect_b32 s36, s24, s8
	s_cselect_b32 s35, s27, s3
	s_cselect_b32 s34, s26, s2
	s_add_i32 s60, 0, 0x14000
	v_add_u32_e32 v142, s53, v204
	v_add_u32_e32 v180, s60, v204
	ds_read_b128 v[130:133], v142
	ds_read_b128 v[134:137], v142 offset:1024
	ds_read_b128 v[138:141], v142 offset:2048
	ds_read_b128 v[142:145], v142 offset:3072
	ds_read_b128 v[146:149], v180
	ds_read_b128 v[150:153], v180 offset:1024
	ds_read_b128 v[154:157], v180 offset:2048
	ds_read_b128 v[180:183], v180 offset:3072
	v_lshl_add_u64 v[222:223], s[30:31], 0, v[166:167]
	s_add_i32 m0, s46, 0xc000
	ds_read_b128 v[184:187], v206
	ds_read_b128 v[188:191], v206 offset:1024
	ds_read_b128 v[192:195], v206 offset:2048
	ds_read_b128 v[196:199], v206 offset:3072
	ds_read_b128 v[200:203], v206 offset:4096
	ds_read_b128 v[208:211], v206 offset:5120
	ds_read_b128 v[212:215], v206 offset:6144
	ds_read_b128 v[216:219], v206 offset:7168
	global_load_lds_dwordx4 v[222:223], off
	v_lshl_add_u64 v[222:223], s[30:31], 0, v[168:169]
	s_add_i32 m0, s46, 0xe000
	s_nop 0
	global_load_lds_dwordx4 v[222:223], off
	s_waitcnt vmcnt(8)
	s_waitcnt lgkmcnt(0)
	s_barrier
	s_setprio 1
	v_mfma_f32_16x16x32_bf16 v[126:129], v[130:133], v[184:187], v[126:129]
	v_mfma_f32_16x16x32_bf16 v[122:125], v[138:141], v[184:187], v[122:125]
	v_mfma_f32_16x16x32_bf16 v[110:113], v[130:133], v[192:195], v[110:113]
	v_mfma_f32_16x16x32_bf16 v[106:109], v[138:141], v[192:195], v[106:109]
	v_mfma_f32_16x16x32_bf16 v[94:97], v[130:133], v[200:203], v[94:97]
	v_mfma_f32_16x16x32_bf16 v[90:93], v[138:141], v[200:203], v[90:93]
	v_mfma_f32_16x16x32_bf16 v[78:81], v[130:133], v[212:215], v[78:81]
	v_mfma_f32_16x16x32_bf16 v[74:77], v[138:141], v[212:215], v[74:77]
	v_mfma_f32_16x16x32_bf16 v[126:129], v[134:137], v[188:191], v[126:129]
	v_mfma_f32_16x16x32_bf16 v[122:125], v[142:145], v[188:191], v[122:125]
	v_mfma_f32_16x16x32_bf16 v[110:113], v[134:137], v[196:199], v[110:113]
	v_mfma_f32_16x16x32_bf16 v[106:109], v[142:145], v[196:199], v[106:109]
	v_mfma_f32_16x16x32_bf16 v[94:97], v[134:137], v[208:211], v[94:97]
	v_mfma_f32_16x16x32_bf16 v[90:93], v[142:145], v[208:211], v[90:93]
	v_mfma_f32_16x16x32_bf16 v[78:81], v[134:137], v[216:219], v[78:81]
	v_mfma_f32_16x16x32_bf16 v[74:77], v[142:145], v[216:219], v[74:77]
	s_setprio 0
	s_setprio 1
	v_mfma_f32_16x16x32_bf16 v[118:121], v[146:149], v[184:187], v[118:121]
	v_mfma_f32_16x16x32_bf16 v[114:117], v[154:157], v[184:187], v[114:117]
	v_mfma_f32_16x16x32_bf16 v[102:105], v[146:149], v[192:195], v[102:105]
	v_mfma_f32_16x16x32_bf16 v[98:101], v[154:157], v[192:195], v[98:101]
	v_mfma_f32_16x16x32_bf16 v[86:89], v[146:149], v[200:203], v[86:89]
	v_mfma_f32_16x16x32_bf16 v[82:85], v[154:157], v[200:203], v[82:85]
	v_mfma_f32_16x16x32_bf16 v[70:73], v[146:149], v[212:215], v[70:73]
	v_mfma_f32_16x16x32_bf16 v[66:69], v[154:157], v[212:215], v[66:69]
	v_mfma_f32_16x16x32_bf16 v[118:121], v[150:153], v[188:191], v[118:121]
	v_mfma_f32_16x16x32_bf16 v[114:117], v[180:183], v[188:191], v[114:117]
	v_mfma_f32_16x16x32_bf16 v[102:105], v[150:153], v[196:199], v[102:105]
	v_mfma_f32_16x16x32_bf16 v[98:101], v[180:183], v[196:199], v[98:101]
	v_mfma_f32_16x16x32_bf16 v[86:89], v[150:153], v[208:211], v[86:89]
	v_mfma_f32_16x16x32_bf16 v[82:85], v[180:183], v[208:211], v[82:85]
	v_mfma_f32_16x16x32_bf16 v[70:73], v[150:153], v[216:219], v[70:73]
	v_mfma_f32_16x16x32_bf16 v[66:69], v[180:183], v[216:219], v[66:69]
	s_setprio 0
	s_barrier
	s_add_i32 s30, s53, s40
	v_lshl_add_u64 v[222:223], s[34:35], 0, v[0:1]
	s_mov_b32 m0, s30
	ds_read_b128 v[184:187], v206 offset:16384
	ds_read_b128 v[188:191], v206 offset:17408
	ds_read_b128 v[192:195], v206 offset:18432
	ds_read_b128 v[196:199], v206 offset:19456
	ds_read_b128 v[200:203], v206 offset:20480
	ds_read_b128 v[208:211], v206 offset:21504
	ds_read_b128 v[212:215], v206 offset:22528
	ds_read_b128 v[216:219], v206 offset:23552
	global_load_lds_dwordx4 v[222:223], off
	s_add_i32 m0, s30, 0x2000
	s_add_u32 s30, s34, 0xb0000
	v_lshl_add_u64 v[232:233], s[34:35], 0, v[162:163]
	s_addc_u32 s31, s35, 0
	s_add_i32 s53, s60, s40
	global_load_lds_dwordx4 v[232:233], off
	v_lshl_add_u64 v[236:237], s[30:31], 0, v[0:1]
	s_mov_b32 m0, s53
	v_lshl_add_u64 v[238:239], s[36:37], 0, v[160:161]
	global_load_lds_dwordx4 v[236:237], off
	v_lshl_add_u64 v[236:237], s[30:31], 0, v[162:163]
	s_add_i32 m0, s53, 0x2000
	s_nop 0
	global_load_lds_dwordx4 v[236:237], off
	v_lshl_add_u64 v[236:237], s[36:37], 0, v[158:159]
	s_mov_b32 m0, s46
	s_nop 0
	global_load_lds_dwordx4 v[236:237], off
	s_mov_b32 m0, s47
	s_nop 0
	global_load_lds_dwordx4 v[238:239], off
	s_waitcnt vmcnt(8)
	s_waitcnt lgkmcnt(0)
	s_barrier
	s_setprio 1
	v_mfma_f32_16x16x32_bf16 v[62:65], v[130:133], v[184:187], v[62:65]
	v_mfma_f32_16x16x32_bf16 v[58:61], v[138:141], v[184:187], v[58:61]
	v_mfma_f32_16x16x32_bf16 v[46:49], v[130:133], v[192:195], v[46:49]
	v_mfma_f32_16x16x32_bf16 v[42:45], v[138:141], v[192:195], v[42:45]
	v_mfma_f32_16x16x32_bf16 v[30:33], v[130:133], v[200:203], v[30:33]
	v_mfma_f32_16x16x32_bf16 v[26:29], v[138:141], v[200:203], v[26:29]
	v_mfma_f32_16x16x32_bf16 v[14:17], v[130:133], v[212:215], v[14:17]
	v_mfma_f32_16x16x32_bf16 v[10:13], v[138:141], v[212:215], v[10:13]
	v_mfma_f32_16x16x32_bf16 v[62:65], v[134:137], v[188:191], v[62:65]
	v_mfma_f32_16x16x32_bf16 v[58:61], v[142:145], v[188:191], v[58:61]
	v_mfma_f32_16x16x32_bf16 v[46:49], v[134:137], v[196:199], v[46:49]
	v_mfma_f32_16x16x32_bf16 v[42:45], v[142:145], v[196:199], v[42:45]
	v_mfma_f32_16x16x32_bf16 v[30:33], v[134:137], v[208:211], v[30:33]
	v_mfma_f32_16x16x32_bf16 v[26:29], v[142:145], v[208:211], v[26:29]
	v_mfma_f32_16x16x32_bf16 v[14:17], v[134:137], v[216:219], v[14:17]
	v_mfma_f32_16x16x32_bf16 v[10:13], v[142:145], v[216:219], v[10:13]
	s_setprio 0
	s_setprio 1
	v_mfma_f32_16x16x32_bf16 v[54:57], v[146:149], v[184:187], v[54:57]
	v_mfma_f32_16x16x32_bf16 v[50:53], v[154:157], v[184:187], v[50:53]
	v_mfma_f32_16x16x32_bf16 v[38:41], v[146:149], v[192:195], v[38:41]
	v_mfma_f32_16x16x32_bf16 v[34:37], v[154:157], v[192:195], v[34:37]
	v_mfma_f32_16x16x32_bf16 v[22:25], v[146:149], v[200:203], v[22:25]
	v_mfma_f32_16x16x32_bf16 v[18:21], v[154:157], v[200:203], v[18:21]
	v_mfma_f32_16x16x32_bf16 v[6:9], v[146:149], v[212:215], v[6:9]
	v_mfma_f32_16x16x32_bf16 v[2:5], v[154:157], v[212:215], v[2:5]
	v_mfma_f32_16x16x32_bf16 v[54:57], v[150:153], v[188:191], v[54:57]
	v_mfma_f32_16x16x32_bf16 v[50:53], v[180:183], v[188:191], v[50:53]
	v_mfma_f32_16x16x32_bf16 v[38:41], v[150:153], v[196:199], v[38:41]
	v_mfma_f32_16x16x32_bf16 v[34:37], v[180:183], v[196:199], v[34:37]
	v_mfma_f32_16x16x32_bf16 v[22:25], v[150:153], v[208:211], v[22:25]
	v_mfma_f32_16x16x32_bf16 v[18:21], v[180:183], v[208:211], v[18:21]
	v_mfma_f32_16x16x32_bf16 v[6:9], v[150:153], v[216:219], v[6:9]
	v_mfma_f32_16x16x32_bf16 v[2:5], v[180:183], v[216:219], v[2:5]
	s_setprio 0
	s_barrier
	s_add_i32 s53, 0, 0x18000
	s_add_i32 s60, 0, 0x1c000
	v_add_u32_e32 v142, s53, v204
	v_add_u32_e32 v180, s60, v204
	ds_read_b128 v[130:133], v142
	ds_read_b128 v[134:137], v142 offset:1024
	ds_read_b128 v[138:141], v142 offset:2048
	ds_read_b128 v[142:145], v142 offset:3072
	ds_read_b128 v[146:149], v180
	ds_read_b128 v[150:153], v180 offset:1024
	ds_read_b128 v[154:157], v180 offset:2048
	ds_read_b128 v[180:183], v180 offset:3072
	s_add_u32 s30, s36, 0xb0000
	s_addc_u32 s31, s37, 0
	s_mov_b32 m0, s52
	v_lshl_add_u64 v[240:241], s[30:31], 0, v[158:159]
	ds_read_b128 v[184:187], v206 offset:32768
	ds_read_b128 v[188:191], v206 offset:33792
	ds_read_b128 v[192:195], v206 offset:34816
	ds_read_b128 v[196:199], v206 offset:35840
	ds_read_b128 v[200:203], v206 offset:36864
	ds_read_b128 v[208:211], v206 offset:37888
	ds_read_b128 v[212:215], v206 offset:38912
	ds_read_b128 v[216:219], v206 offset:39936
	global_load_lds_dwordx4 v[240:241], off
	v_lshl_add_u64 v[240:241], s[30:31], 0, v[160:161]
	s_mov_b32 m0, s56
	s_nop 0
	global_load_lds_dwordx4 v[240:241], off
	s_waitcnt vmcnt(8)
	s_waitcnt lgkmcnt(0)
	s_barrier
	s_setprio 1
	v_mfma_f32_16x16x32_bf16 v[126:129], v[130:133], v[184:187], v[126:129]
	v_mfma_f32_16x16x32_bf16 v[122:125], v[138:141], v[184:187], v[122:125]
	v_mfma_f32_16x16x32_bf16 v[110:113], v[130:133], v[192:195], v[110:113]
	v_mfma_f32_16x16x32_bf16 v[106:109], v[138:141], v[192:195], v[106:109]
	v_mfma_f32_16x16x32_bf16 v[94:97], v[130:133], v[200:203], v[94:97]
	v_mfma_f32_16x16x32_bf16 v[90:93], v[138:141], v[200:203], v[90:93]
	v_mfma_f32_16x16x32_bf16 v[78:81], v[130:133], v[212:215], v[78:81]
	v_mfma_f32_16x16x32_bf16 v[74:77], v[138:141], v[212:215], v[74:77]
	v_mfma_f32_16x16x32_bf16 v[126:129], v[134:137], v[188:191], v[126:129]
	v_mfma_f32_16x16x32_bf16 v[122:125], v[142:145], v[188:191], v[122:125]
	v_mfma_f32_16x16x32_bf16 v[110:113], v[134:137], v[196:199], v[110:113]
	v_mfma_f32_16x16x32_bf16 v[106:109], v[142:145], v[196:199], v[106:109]
	v_mfma_f32_16x16x32_bf16 v[94:97], v[134:137], v[208:211], v[94:97]
	v_mfma_f32_16x16x32_bf16 v[90:93], v[142:145], v[208:211], v[90:93]
	v_mfma_f32_16x16x32_bf16 v[78:81], v[134:137], v[216:219], v[78:81]
	v_mfma_f32_16x16x32_bf16 v[74:77], v[142:145], v[216:219], v[74:77]
	s_setprio 0
	s_setprio 1
	v_mfma_f32_16x16x32_bf16 v[118:121], v[146:149], v[184:187], v[118:121]
	v_mfma_f32_16x16x32_bf16 v[114:117], v[154:157], v[184:187], v[114:117]
	v_mfma_f32_16x16x32_bf16 v[102:105], v[146:149], v[192:195], v[102:105]
	v_mfma_f32_16x16x32_bf16 v[98:101], v[154:157], v[192:195], v[98:101]
	v_mfma_f32_16x16x32_bf16 v[86:89], v[146:149], v[200:203], v[86:89]
	v_mfma_f32_16x16x32_bf16 v[82:85], v[154:157], v[200:203], v[82:85]
	v_mfma_f32_16x16x32_bf16 v[70:73], v[146:149], v[212:215], v[70:73]
	v_mfma_f32_16x16x32_bf16 v[66:69], v[154:157], v[212:215], v[66:69]
	v_mfma_f32_16x16x32_bf16 v[118:121], v[150:153], v[188:191], v[118:121]
	v_mfma_f32_16x16x32_bf16 v[114:117], v[180:183], v[188:191], v[114:117]
	v_mfma_f32_16x16x32_bf16 v[102:105], v[150:153], v[196:199], v[102:105]
	v_mfma_f32_16x16x32_bf16 v[98:101], v[180:183], v[196:199], v[98:101]
	v_mfma_f32_16x16x32_bf16 v[86:89], v[150:153], v[208:211], v[86:89]
	v_mfma_f32_16x16x32_bf16 v[82:85], v[180:183], v[208:211], v[82:85]
	v_mfma_f32_16x16x32_bf16 v[70:73], v[150:153], v[216:219], v[70:73]
	v_mfma_f32_16x16x32_bf16 v[66:69], v[180:183], v[216:219], v[66:69]
	s_setprio 0
	s_barrier
	s_add_i32 s30, s53, s40
	v_lshl_add_u64 v[222:223], v[222:223], 0, s[54:55]
	s_mov_b32 m0, s30
	ds_read_b128 v[184:187], v206 offset:49152
	ds_read_b128 v[188:191], v206 offset:50176
	ds_read_b128 v[192:195], v206 offset:51200
	ds_read_b128 v[196:199], v206 offset:52224
	ds_read_b128 v[200:203], v206 offset:53248
	ds_read_b128 v[208:211], v206 offset:54272
	ds_read_b128 v[212:215], v206 offset:55296
	ds_read_b128 v[216:219], v206 offset:56320
	global_load_lds_dwordx4 v[222:223], off
	s_add_i32 m0, s30, 0x2000
	s_add_u32 s30, s34, 0xb0080
	v_lshl_add_u64 v[222:223], v[232:233], 0, s[54:55]
	s_addc_u32 s31, s35, 0
	s_add_i32 s34, s60, s40
	global_load_lds_dwordx4 v[222:223], off
	v_lshl_add_u64 v[222:223], s[30:31], 0, v[0:1]
	s_mov_b32 m0, s34
	s_nop 0
	global_load_lds_dwordx4 v[222:223], off
	v_lshl_add_u64 v[222:223], s[30:31], 0, v[162:163]
	s_add_i32 m0, s34, 0x2000
	s_nop 0
	global_load_lds_dwordx4 v[222:223], off
	v_lshl_add_u64 v[222:223], v[236:237], 0, s[54:55]
	s_mov_b32 m0, s58
	s_nop 0
	global_load_lds_dwordx4 v[222:223], off
	v_lshl_add_u64 v[222:223], v[238:239], 0, s[54:55]
	s_mov_b32 m0, s59
	s_nop 0
	global_load_lds_dwordx4 v[222:223], off
	s_waitcnt vmcnt(8)
	s_waitcnt lgkmcnt(0)
	s_barrier
	s_setprio 1
	v_mfma_f32_16x16x32_bf16 v[62:65], v[130:133], v[184:187], v[62:65]
	v_mfma_f32_16x16x32_bf16 v[58:61], v[138:141], v[184:187], v[58:61]
	v_mfma_f32_16x16x32_bf16 v[46:49], v[130:133], v[192:195], v[46:49]
	v_mfma_f32_16x16x32_bf16 v[42:45], v[138:141], v[192:195], v[42:45]
	v_mfma_f32_16x16x32_bf16 v[30:33], v[130:133], v[200:203], v[30:33]
	v_mfma_f32_16x16x32_bf16 v[26:29], v[138:141], v[200:203], v[26:29]
	v_mfma_f32_16x16x32_bf16 v[14:17], v[130:133], v[212:215], v[14:17]
	v_mfma_f32_16x16x32_bf16 v[10:13], v[138:141], v[212:215], v[10:13]
	v_mfma_f32_16x16x32_bf16 v[62:65], v[134:137], v[188:191], v[62:65]
	v_mfma_f32_16x16x32_bf16 v[58:61], v[142:145], v[188:191], v[58:61]
	v_mfma_f32_16x16x32_bf16 v[46:49], v[134:137], v[196:199], v[46:49]
	v_mfma_f32_16x16x32_bf16 v[42:45], v[142:145], v[196:199], v[42:45]
	v_mfma_f32_16x16x32_bf16 v[30:33], v[134:137], v[208:211], v[30:33]
	v_mfma_f32_16x16x32_bf16 v[26:29], v[142:145], v[208:211], v[26:29]
	v_mfma_f32_16x16x32_bf16 v[14:17], v[134:137], v[216:219], v[14:17]
	v_mfma_f32_16x16x32_bf16 v[10:13], v[142:145], v[216:219], v[10:13]
	s_setprio 0
	s_setprio 1
	v_mfma_f32_16x16x32_bf16 v[54:57], v[146:149], v[184:187], v[54:57]
	v_mfma_f32_16x16x32_bf16 v[50:53], v[154:157], v[184:187], v[50:53]
	v_mfma_f32_16x16x32_bf16 v[38:41], v[146:149], v[192:195], v[38:41]
	v_mfma_f32_16x16x32_bf16 v[34:37], v[154:157], v[192:195], v[34:37]
	v_mfma_f32_16x16x32_bf16 v[22:25], v[146:149], v[200:203], v[22:25]
	v_mfma_f32_16x16x32_bf16 v[18:21], v[154:157], v[200:203], v[18:21]
	v_mfma_f32_16x16x32_bf16 v[6:9], v[146:149], v[212:215], v[6:9]
	v_mfma_f32_16x16x32_bf16 v[2:5], v[154:157], v[212:215], v[2:5]
	v_mfma_f32_16x16x32_bf16 v[54:57], v[150:153], v[188:191], v[54:57]
	v_mfma_f32_16x16x32_bf16 v[50:53], v[180:183], v[188:191], v[50:53]
	v_mfma_f32_16x16x32_bf16 v[38:41], v[150:153], v[196:199], v[38:41]
	v_mfma_f32_16x16x32_bf16 v[34:37], v[180:183], v[196:199], v[34:37]
	v_mfma_f32_16x16x32_bf16 v[22:25], v[150:153], v[208:211], v[22:25]
	v_mfma_f32_16x16x32_bf16 v[18:21], v[180:183], v[208:211], v[18:21]
	v_mfma_f32_16x16x32_bf16 v[6:9], v[150:153], v[216:219], v[6:9]
	v_mfma_f32_16x16x32_bf16 v[2:5], v[180:183], v[216:219], v[2:5]
	s_setprio 0
	s_barrier
	s_add_i32 s29, s29, 2
	s_add_u32 s2, s2, 0x100
	s_addc_u32 s3, s3, 0
	s_cmp_gt_u32 s29, 41
	s_mov_b64 s[30:31], s[8:9]
	s_cbranch_scc0 .LBB0_1197
	s_and_b64 vcc, exec, s[20:21]
	s_cbranch_vccz .LBB0_1200
	s_barrier
